# LN phases no longer store normalized x (except final layer): per-row mean/rstd saved to a dead ws region and the consuming RES-GEMM epilogue recomputes fma(g,(x-mu)*rstd,b) with the same op order
# speedup vs baseline: 1.3969x; 1.0172x over previous
.LBB0_154:
	s_add_i32 s4, s15, 0xffff8000
	v_mov_b32_e32 v64, v182
	s_waitcnt vmcnt(0)
	s_waitcnt vmcnt(0) lgkmcnt(0)
	s_barrier
	s_and_b32 s16, s15, 0x8000
	s_and_b32 s17, s4, 0x8000
	v_or_b32_e32 v71, s17, v121
	v_lshrrev_b32_e32 v65, 4, v64
	v_ashrrev_i32_e32 v66, 3, v64
	v_add_u32_e32 v68, 0x100, v64
	v_lshl_add_u32 v67, v64, 4, s16
	v_add_u32_e32 v69, 0x200, v64
	v_add_u32_e32 v72, s0, v66
	v_bitop3_b32 v73, v65, 7, v64 bitop3:0x48
	v_ashrrev_i32_e32 v74, 3, v68
	s_add_u32 s10, s30, s8
	v_add_u32_e32 v70, 0x300, v64
	v_lshl_add_u32 v68, v68, 4, s16
	v_ashrrev_i32_e32 v75, 3, v69
	v_lshl_add_u32 v69, v69, 4, s16
	v_add_u32_e32 v77, 0x4000, v67
	v_add3_u32 v84, v71, v122, v123
	v_add3_u32 v80, v71, v124, v123
	v_mad_i64_i32 v[64:65], s[18:19], v72, s64, 0
	v_lshlrev_b32_e32 v81, 4, v73
	v_add_u32_e32 v71, s0, v74
	s_addc_u32 s11, s31, s9
	v_ashrrev_i32_e32 v76, 3, v70
	v_lshl_add_u32 v70, v70, 4, s16
	v_readfirstlane_b32 s5, v68
	v_add_u32_e32 v72, s0, v75
	v_readfirstlane_b32 s20, v69
	v_readfirstlane_b32 s22, v77
	v_add_u32_e32 v77, 0x4000, v68
	v_add_u32_e32 v79, 0x4000, v69
	v_or_b32_e32 v64, v64, v81
	v_mad_i64_i32 v[68:69], s[18:19], v71, s64, 0
	v_readfirstlane_b32 s4, v67
	v_add_u32_e32 v73, s0, v76
	v_readfirstlane_b32 s21, v70
	v_add_u32_e32 v83, 0x4000, v70
	v_mad_i64_i32 v[70:71], s[18:19], v72, s64, 0
	v_lshl_add_u64 v[64:65], s[10:11], 0, v[64:65]
	v_or_b32_e32 v68, v68, v81
	v_add_u32_e32 v66, s14, v66
	v_mad_i64_i32 v[72:73], s[18:19], v73, s64, 0
	v_or_b32_e32 v70, v70, v81
	v_lshl_add_u64 v[64:65], v[64:65], 0, s[88:89]
	v_lshl_add_u64 v[68:69], s[10:11], 0, v[68:69]
	s_mov_b32 m0, s4
	v_mad_i64_i32 v[66:67], s[18:19], v66, s64, 0
	v_add_u32_e32 v74, s14, v74
	v_or_b32_e32 v72, v72, v81
	v_lshl_add_u64 v[70:71], s[10:11], 0, v[70:71]
	global_load_lds_dwordx4 v[64:65], off
	v_lshl_add_u64 v[64:65], v[68:69], 0, s[88:89]
	s_mov_b32 m0, s5
	v_add_u32_e32 v78, s14, v75
	v_or_b32_e32 v66, v66, v81
	v_mad_i64_i32 v[74:75], s[18:19], v74, s64, 0
	v_lshl_add_u64 v[72:73], s[10:11], 0, v[72:73]
	v_lshl_add_u64 v[68:69], v[70:71], 0, s[88:89]
	global_load_lds_dwordx4 v[64:65], off
	s_mov_b32 m0, s20
	v_add_u32_e32 v82, s14, v76
	v_readfirstlane_b32 s23, v77
	v_mad_i64_i32 v[76:77], s[18:19], v78, s64, 0
	v_lshl_add_u64 v[66:67], s[10:11], 0, v[66:67]
	v_or_b32_e32 v74, v74, v81
	v_lshl_add_u64 v[70:71], v[72:73], 0, s[88:89]
	global_load_lds_dwordx4 v[68:69], off
	s_mov_b32 m0, s21
	v_readfirstlane_b32 s36, v79
	v_mad_i64_i32 v[78:79], s[18:19], v82, s64, 0
	v_or_b32_e32 v76, v76, v81
	v_lshl_add_u64 v[66:67], v[66:67], 0, s[78:79]
	v_lshl_add_u64 v[74:75], s[10:11], 0, v[74:75]
	global_load_lds_dwordx4 v[70:71], off
	s_mov_b32 m0, s22
	v_or_b32_e32 v78, v78, v81
	v_lshl_add_u64 v[76:77], s[10:11], 0, v[76:77]
	v_lshl_add_u64 v[72:73], v[74:75], 0, s[78:79]
	global_load_lds_dwordx4 v[66:67], off
	s_mov_b32 m0, s23
	v_readfirstlane_b32 s18, v83
	v_lshl_add_u64 v[78:79], s[10:11], 0, v[78:79]
	v_lshl_add_u64 v[74:75], v[76:77], 0, s[78:79]
	global_load_lds_dwordx4 v[72:73], off
	s_mov_b32 m0, s36
	v_lshl_add_u64 v[76:77], v[78:79], 0, s[78:79]
	global_load_lds_dwordx4 v[74:75], off
	s_mov_b32 m0, s18
	s_add_u32 s8, s8, 0x80
	global_load_lds_dwordx4 v[76:77], off
	ds_read_b128 v[64:67], v84
	ds_read_b128 v[68:71], v80 offset:16384
	ds_read_b128 v[72:75], v80 offset:18432
	ds_read_b128 v[76:79], v80 offset:20480
	ds_read_b128 v[80:83], v80 offset:22528
	s_waitcnt lgkmcnt(0)
	v_mfma_f32_16x16x32_f16 v[60:63], v[64:67], v[68:71], v[60:63]
	s_addc_u32 s9, s9, 0
	s_add_i32 s15, s15, 0x8000
	s_cmpk_eq_i32 s8, 0x1580
	v_mfma_f32_16x16x32_f16 v[56:59], v[64:67], v[72:75], v[56:59]
	v_mfma_f32_16x16x32_f16 v[52:55], v[64:67], v[76:79], v[52:55]
	v_mfma_f32_16x16x32_f16 v[48:51], v[64:67], v[80:83], v[48:51]
	ds_read_b128 v[64:67], v84 offset:2048
	s_waitcnt lgkmcnt(0)
	v_mfma_f32_16x16x32_f16 v[44:47], v[64:67], v[68:71], v[44:47]
	v_mfma_f32_16x16x32_f16 v[40:43], v[64:67], v[72:75], v[40:43]
	v_mfma_f32_16x16x32_f16 v[32:35], v[64:67], v[76:79], v[32:35]
	v_mfma_f32_16x16x32_f16 v[28:31], v[64:67], v[80:83], v[28:31]
	ds_read_b128 v[64:67], v84 offset:4096
	s_waitcnt lgkmcnt(0)
	v_mfma_f32_16x16x32_f16 v[24:27], v[64:67], v[68:71], v[24:27]
	v_mfma_f32_16x16x32_f16 v[20:23], v[64:67], v[72:75], v[20:23]
	v_mfma_f32_16x16x32_f16 v[16:19], v[64:67], v[76:79], v[16:19]
	v_mfma_f32_16x16x32_f16 v[12:15], v[64:67], v[80:83], v[12:15]
	ds_read_b128 v[64:67], v84 offset:6144
	s_waitcnt lgkmcnt(0)
	v_mfma_f32_16x16x32_f16 v[8:11], v[64:67], v[68:71], v[8:11]
	v_or_b32_e32 v68, s17, v125
	v_add3_u32 v84, v68, v122, v123
	v_add3_u32 v85, v68, v124, v123
	ds_read_b128 v[68:71], v84
	v_mfma_f32_16x16x32_f16 v[4:7], v[64:67], v[72:75], v[4:7]
	ds_read_b128 v[72:75], v85 offset:18432
	v_mfma_f32_16x16x32_f16 v[0:3], v[64:67], v[76:79], v[0:3]
	ds_read_b128 v[76:79], v85 offset:20480
	v_mfma_f32_16x16x32_f16 v[36:39], v[64:67], v[80:83], v[36:39]
	ds_read_b128 v[64:67], v85 offset:16384
	ds_read_b128 v[80:83], v85 offset:22528
	s_waitcnt lgkmcnt(1)
	v_mfma_f32_16x16x32_f16 v[60:63], v[68:71], v[64:67], v[60:63]
	v_mfma_f32_16x16x32_f16 v[56:59], v[68:71], v[72:75], v[56:59]
	v_mfma_f32_16x16x32_f16 v[52:55], v[68:71], v[76:79], v[52:55]
	s_waitcnt lgkmcnt(0)
	v_mfma_f32_16x16x32_f16 v[48:51], v[68:71], v[80:83], v[48:51]
	ds_read_b128 v[68:71], v84 offset:2048
	s_waitcnt lgkmcnt(0)
	v_mfma_f32_16x16x32_f16 v[44:47], v[68:71], v[64:67], v[44:47]
	v_mfma_f32_16x16x32_f16 v[40:43], v[68:71], v[72:75], v[40:43]
	v_mfma_f32_16x16x32_f16 v[32:35], v[68:71], v[76:79], v[32:35]
	v_mfma_f32_16x16x32_f16 v[28:31], v[68:71], v[80:83], v[28:31]
	ds_read_b128 v[68:71], v84 offset:4096
	s_waitcnt lgkmcnt(0)
	v_mfma_f32_16x16x32_f16 v[24:27], v[68:71], v[64:67], v[24:27]
	v_mfma_f32_16x16x32_f16 v[20:23], v[68:71], v[72:75], v[20:23]
	v_mfma_f32_16x16x32_f16 v[16:19], v[68:71], v[76:79], v[16:19]
	v_mfma_f32_16x16x32_f16 v[12:15], v[68:71], v[80:83], v[12:15]
	ds_read_b128 v[68:71], v84 offset:6144
	s_waitcnt lgkmcnt(0)
	v_mfma_f32_16x16x32_f16 v[8:11], v[68:71], v[64:67], v[8:11]
	v_mfma_f32_16x16x32_f16 v[4:7], v[68:71], v[72:75], v[4:7]
	v_mfma_f32_16x16x32_f16 v[0:3], v[68:71], v[76:79], v[0:3]
	v_mfma_f32_16x16x32_f16 v[36:39], v[68:71], v[80:83], v[36:39]
	s_cbranch_scc0 .LBB0_154
	v_add_u32_e32 v80, s16, v121
	v_add3_u32 v76, v80, v122, v123
	v_add3_u32 v92, v80, v124, v123
	s_waitcnt vmcnt(0)
	s_barrier
	ds_read_b128 v[64:67], v76
	ds_read_b128 v[68:71], v76 offset:2048
	ds_read_b128 v[72:75], v76 offset:4096
	ds_read_b128 v[76:79], v76 offset:6144
	ds_read_b128 v[80:83], v92 offset:16384
	ds_read_b128 v[84:87], v92 offset:18432
	ds_read_b128 v[88:91], v92 offset:20480
	ds_read_b128 v[92:95], v92 offset:22528
	s_waitcnt lgkmcnt(3)
	v_mfma_f32_16x16x32_f16 v[96:99], v[72:75], v[80:83], v[24:27]
	s_ashr_i32 s4, s0, 31
	s_lshr_b32 s4, s4, 19
	s_add_i32 s4, s0, s4
	s_waitcnt lgkmcnt(2)
	v_mfma_f32_16x16x32_f16 v[20:23], v[72:75], v[84:87], v[20:23]
	s_ashr_i32 s8, s4, 13
	s_add_i32 s4, s8, s12
	s_mul_hi_i32 s5, s4, 0x9000
	s_waitcnt lgkmcnt(1)
	v_mfma_f32_16x16x32_f16 v[16:19], v[72:75], v[88:91], v[16:19]
	s_mul_i32 s4, s4, 0x9000
	s_add_u32 s8, s50, s4
	s_addc_u32 s9, s51, s5
	s_waitcnt lgkmcnt(0)
	v_mfma_f32_16x16x32_f16 v[72:75], v[72:75], v[92:95], v[12:15]
	s_add_i32 s13, s13, s59
	s_cmpk_gt_i32 s13, 0x7ff
	s_nop 0
	v_add_u32_e32 v12, s16, v125
	v_add3_u32 v13, v12, v122, v123
	v_add3_u32 v12, v12, v124, v123
	v_mfma_f32_16x16x32_f16 v[60:63], v[64:67], v[80:83], v[60:63]
	v_mfma_f32_16x16x32_f16 v[56:59], v[64:67], v[84:87], v[56:59]
	v_mfma_f32_16x16x32_f16 v[52:55], v[64:67], v[88:91], v[52:55]
	v_mfma_f32_16x16x32_f16 v[48:51], v[64:67], v[92:95], v[48:51]
	v_mfma_f32_16x16x32_f16 v[64:67], v[68:71], v[80:83], v[44:47]
	v_mfma_f32_16x16x32_f16 v[40:43], v[68:71], v[84:87], v[40:43]
	v_mfma_f32_16x16x32_f16 v[32:35], v[68:71], v[88:91], v[32:35]
	v_mfma_f32_16x16x32_f16 v[68:71], v[68:71], v[92:95], v[28:31]
	v_mfma_f32_16x16x32_f16 v[80:83], v[76:79], v[80:83], v[8:11]
	v_mfma_f32_16x16x32_f16 v[84:87], v[76:79], v[84:87], v[4:7]
	v_mfma_f32_16x16x32_f16 v[0:3], v[76:79], v[88:91], v[0:3]
	v_mfma_f32_16x16x32_f16 v[76:79], v[76:79], v[92:95], v[36:39]
	s_nop 0
	ds_read_b128 v[4:7], v13
	ds_read_b128 v[8:11], v13 offset:2048
	ds_read_b128 v[88:91], v13 offset:4096
	ds_read_b128 v[92:95], v13 offset:6144
	ds_read_b128 v[100:103], v12 offset:16384
	ds_read_b128 v[104:107], v12 offset:18432
	ds_read_b128 v[108:111], v12 offset:20480
	ds_read_b128 v[116:119], v12 offset:22528
	s_waitcnt lgkmcnt(3)
	v_mfma_f32_16x16x32_f16 v[60:63], v[4:7], v[100:103], v[60:63]
	s_waitcnt lgkmcnt(2)
	v_mfma_f32_16x16x32_f16 v[44:47], v[4:7], v[104:107], v[56:59]
	s_waitcnt lgkmcnt(1)
	v_mfma_f32_16x16x32_f16 v[28:31], v[4:7], v[108:111], v[52:55]
	s_waitcnt lgkmcnt(0)
	v_mfma_f32_16x16x32_f16 v[12:15], v[4:7], v[116:119], v[48:51]
	v_mfma_f32_16x16x32_f16 v[52:55], v[88:91], v[100:103], v[96:99]
	v_mfma_f32_16x16x32_f16 v[36:39], v[88:91], v[104:107], v[20:23]
	v_mfma_f32_16x16x32_f16 v[20:23], v[88:91], v[108:111], v[16:19]
	v_mfma_f32_16x16x32_f16 v[4:7], v[88:91], v[116:119], v[72:75]
	v_add_u32_e32 v90, s0, v120
	v_or_b32_e32 v88, s14, v115
	v_ashrrev_i32_e32 v89, 31, v88
	v_mfma_f32_16x16x32_f16 v[56:59], v[8:11], v[100:103], v[64:67]
	v_ashrrev_i32_e32 v91, 31, v90
	v_or_b32_e32 v98, 33, v90
	v_ashrrev_i32_e32 v99, 31, v98
	v_or_b32_e32 v64, 48, v90
	v_ashrrev_i32_e32 v65, 31, v64
	v_mfma_f32_16x16x32_f16 v[40:43], v[8:11], v[104:107], v[40:43]
	v_lshlrev_b64 v[98:99], 10, v[98:99]
	v_lshl_add_u64 v[98:99], v[98:99], 0, v[88:89]
	v_mfma_f32_16x16x32_f16 v[24:27], v[8:11], v[108:111], v[32:35]
	v_mfma_f32_16x16x32_f16 v[32:35], v[92:95], v[104:107], v[84:87]
	v_lshlrev_b64 v[104:105], 10, v[64:65]
	v_lshl_add_u64 v[64:65], v[88:89], 2, s[8:9]
	v_add_co_u32_e32 v66, vcc, s48, v64
	v_mfma_f32_16x16x32_f16 v[8:11], v[8:11], v[116:119], v[68:71]
	s_nop 0
	v_addc_co_u32_e32 v67, vcc, 0, v65, vcc
	global_load_dword v64, v[66:67], off
	v_mfma_f32_16x16x32_f16 v[16:19], v[92:95], v[108:111], v[0:3]
	v_or_b32_e32 v106, 35, v90
	v_ashrrev_i32_e32 v107, 31, v106
	v_lshlrev_b64 v[106:107], 10, v[106:107]
	v_mfma_f32_16x16x32_f16 v[0:3], v[92:95], v[116:119], v[76:79]
	v_lshl_add_u64 v[106:107], v[106:107], 0, v[88:89]
	v_lshlrev_b64 v[108:109], 2, v[106:107]
	v_lshl_add_u64 v[106:107], s[2:3], 0, v[108:109]
	v_mfma_f32_16x16x32_f16 v[48:51], v[92:95], v[100:103], v[80:83]
	v_lshlrev_b32_e32 v68, 2, v88
	v_lshl_add_u32 v65, v90, 12, v68
	v_add_u32_e32 v69, 0x1000, v65
	v_add_u32_e32 v70, 0x3000, v65
	v_add_u32_e32 v71, 0x11000, v65
	v_add_u32_e32 v72, 0x13000, v65
	v_add_u32_e32 v73, 0x21000, v65
	v_add_u32_e32 v74, 0x23000, v65
	v_add_u32_e32 v75, 0x31000, v65
	v_add_u32_e32 v76, 0x33000, v65
	v_lshlrev_b32_e32 v176, 3, v90
	v_add_u32_e32 v176, 0x1e200000, v176
	v_add_u32_e32 v177, 0x2000, v68
	v_mov_b32_e32 v178, s71
	v_cmp_ne_u32_e64 s[98:99], 0, v178
	global_load_dwordx2 v[136:137], v176, s[30:31] offset:0
	global_load_dwordx2 v[138:139], v176, s[30:31] offset:8
	global_load_dwordx2 v[140:141], v176, s[30:31] offset:16
	global_load_dwordx2 v[142:143], v176, s[30:31] offset:24
	global_load_dwordx2 v[144:145], v176, s[30:31] offset:128
	global_load_dwordx2 v[146:147], v176, s[30:31] offset:136
	global_load_dwordx2 v[148:149], v176, s[30:31] offset:144
	global_load_dwordx2 v[150:151], v176, s[30:31] offset:152
	global_load_dwordx2 v[152:153], v176, s[30:31] offset:256
	global_load_dwordx2 v[154:155], v176, s[30:31] offset:264
	global_load_dwordx2 v[156:157], v176, s[30:31] offset:272
	global_load_dwordx2 v[158:159], v176, s[30:31] offset:280
	global_load_dwordx2 v[160:161], v176, s[30:31] offset:384
	global_load_dwordx2 v[162:163], v176, s[30:31] offset:392
	global_load_dwordx2 v[164:165], v176, s[30:31] offset:400
	global_load_dwordx2 v[166:167], v176, s[30:31] offset:408
	global_load_dword v168, v177, s[24:25] offset:0
	global_load_dword v172, v177, s[26:27] offset:0
	global_load_dword v169, v177, s[24:25] offset:64
	global_load_dword v173, v177, s[26:27] offset:64
	global_load_dword v170, v177, s[24:25] offset:128
	global_load_dword v174, v177, s[26:27] offset:128
	global_load_dword v171, v177, s[24:25] offset:192
	global_load_dword v175, v177, s[26:27] offset:192
	global_load_dword v77, v[66:67], off offset:0
	global_load_dword v78, v[66:67], off offset:64
	global_load_dword v79, v[66:67], off offset:128
	global_load_dword v80, v[66:67], off offset:192
	global_load_dword v81, v69, s[2:3] offset:-4096
	global_load_dword v82, v69, s[2:3] offset:0
	global_load_dword v83, v70, s[2:3] offset:-4096
	global_load_dword v84, v70, s[2:3] offset:0
	global_load_dword v85, v71, s[2:3] offset:-4096
	global_load_dword v86, v71, s[2:3] offset:0
	global_load_dword v87, v72, s[2:3] offset:-4096
	global_load_dword v89, v72, s[2:3] offset:0
	global_load_dword v91, v73, s[2:3] offset:-4096
	global_load_dword v92, v73, s[2:3] offset:0
	global_load_dword v93, v74, s[2:3] offset:-4096
	global_load_dword v94, v74, s[2:3] offset:0
	global_load_dword v95, v75, s[2:3] offset:-4096
	global_load_dword v96, v75, s[2:3] offset:0
	global_load_dword v97, v76, s[2:3] offset:-4096
	global_load_dword v98, v76, s[2:3] offset:0
	global_load_dword v99, v69, s[2:3] offset:-4032
	global_load_dword v100, v69, s[2:3] offset:64
	global_load_dword v101, v70, s[2:3] offset:-4032
	global_load_dword v102, v70, s[2:3] offset:64
	global_load_dword v103, v71, s[2:3] offset:-4032
	global_load_dword v104, v71, s[2:3] offset:64
	global_load_dword v105, v72, s[2:3] offset:-4032
	global_load_dword v106, v72, s[2:3] offset:64
	global_load_dword v107, v73, s[2:3] offset:-4032
	global_load_dword v108, v73, s[2:3] offset:64
	global_load_dword v109, v74, s[2:3] offset:-4032
	global_load_dword v110, v74, s[2:3] offset:64
	global_load_dword v111, v75, s[2:3] offset:-4032
	global_load_dword v112, v75, s[2:3] offset:64
	global_load_dword v116, v76, s[2:3] offset:-4032
	global_load_dword v117, v76, s[2:3] offset:64
	s_waitcnt vmcnt(32)
	v_add_f32_e32 v77, 1.0, v77
	v_add_f32_e32 v78, 1.0, v78
	v_add_f32_e32 v79, 1.0, v79
	v_add_f32_e32 v80, 1.0, v80
	v_mul_f32_e32 v77, 0.5, v77
	v_mul_f32_e32 v78, 0.5, v78
	v_mul_f32_e32 v79, 0.5, v79
	v_mul_f32_e32 v80, 0.5, v80
	s_waitcnt vmcnt(31)
	v_sub_f32_e32 v179, v81, v136
	v_mul_f32_e32 v179, v179, v137
	v_fma_f32 v179, v168, v179, v172
	v_cndmask_b32_e64 v81, v81, v179, s[98:99]
	v_mul_f32_e32 v60, v60, v77
	v_fmac_f32_e32 v60, 0x3fb504f3, v81
	global_load_dword v81, v69, s[2:3] offset:-3968
	global_store_dword v69, v60, s[28:29] offset:-4096
	s_waitcnt vmcnt(32)
	v_sub_f32_e32 v179, v82, v138
	v_mul_f32_e32 v179, v179, v139
	v_fma_f32 v179, v168, v179, v172
	v_cndmask_b32_e64 v82, v82, v179, s[98:99]
	v_mul_f32_e32 v61, v61, v77
	v_fmac_f32_e32 v61, 0x3fb504f3, v82
	global_load_dword v82, v69, s[2:3] offset:128
	global_store_dword v69, v61, s[28:29] offset:0
	s_waitcnt vmcnt(33)
	v_sub_f32_e32 v179, v83, v140
	v_mul_f32_e32 v179, v179, v141
	v_fma_f32 v179, v168, v179, v172
	v_cndmask_b32_e64 v83, v83, v179, s[98:99]
	v_mul_f32_e32 v62, v62, v77
	v_fmac_f32_e32 v62, 0x3fb504f3, v83
	global_load_dword v83, v70, s[2:3] offset:-3968
	global_store_dword v70, v62, s[28:29] offset:-4096
	s_waitcnt vmcnt(34)
	v_sub_f32_e32 v179, v84, v142
	v_mul_f32_e32 v179, v179, v143
	v_fma_f32 v179, v168, v179, v172
	v_cndmask_b32_e64 v84, v84, v179, s[98:99]
	v_mul_f32_e32 v63, v63, v77
	v_fmac_f32_e32 v63, 0x3fb504f3, v84
	global_load_dword v84, v70, s[2:3] offset:128
	global_store_dword v70, v63, s[28:29] offset:0
	s_waitcnt vmcnt(35)
	v_sub_f32_e32 v179, v85, v144
	v_mul_f32_e32 v179, v179, v145
	v_fma_f32 v179, v168, v179, v172
	v_cndmask_b32_e64 v85, v85, v179, s[98:99]
	v_mul_f32_e32 v56, v56, v77
	v_fmac_f32_e32 v56, 0x3fb504f3, v85
	global_load_dword v85, v71, s[2:3] offset:-3968
	global_store_dword v71, v56, s[28:29] offset:-4096
	s_waitcnt vmcnt(36)
	v_sub_f32_e32 v179, v86, v146
	v_mul_f32_e32 v179, v179, v147
	v_fma_f32 v179, v168, v179, v172
	v_cndmask_b32_e64 v86, v86, v179, s[98:99]
	v_mul_f32_e32 v57, v57, v77
	v_fmac_f32_e32 v57, 0x3fb504f3, v86
	global_load_dword v86, v71, s[2:3] offset:128
	global_store_dword v71, v57, s[28:29] offset:0
	s_waitcnt vmcnt(37)
	v_sub_f32_e32 v179, v87, v148
	v_mul_f32_e32 v179, v179, v149
	v_fma_f32 v179, v168, v179, v172
	v_cndmask_b32_e64 v87, v87, v179, s[98:99]
	v_mul_f32_e32 v58, v58, v77
	v_fmac_f32_e32 v58, 0x3fb504f3, v87
	global_load_dword v87, v72, s[2:3] offset:-3968
	global_store_dword v72, v58, s[28:29] offset:-4096
	s_waitcnt vmcnt(38)
	v_sub_f32_e32 v179, v89, v150
	v_mul_f32_e32 v179, v179, v151
	v_fma_f32 v179, v168, v179, v172
	v_cndmask_b32_e64 v89, v89, v179, s[98:99]
	v_mul_f32_e32 v59, v59, v77
	v_fmac_f32_e32 v59, 0x3fb504f3, v89
	global_load_dword v89, v72, s[2:3] offset:128
	global_store_dword v72, v59, s[28:29] offset:0
	s_waitcnt vmcnt(39)
	v_sub_f32_e32 v179, v91, v152
	v_mul_f32_e32 v179, v179, v153
	v_fma_f32 v179, v168, v179, v172
	v_cndmask_b32_e64 v91, v91, v179, s[98:99]
	v_mul_f32_e32 v52, v52, v77
	v_fmac_f32_e32 v52, 0x3fb504f3, v91
	global_load_dword v91, v73, s[2:3] offset:-3968
	global_store_dword v73, v52, s[28:29] offset:-4096
	s_waitcnt vmcnt(40)
	v_sub_f32_e32 v179, v92, v154
	v_mul_f32_e32 v179, v179, v155
	v_fma_f32 v179, v168, v179, v172
	v_cndmask_b32_e64 v92, v92, v179, s[98:99]
	v_mul_f32_e32 v53, v53, v77
	v_fmac_f32_e32 v53, 0x3fb504f3, v92
	global_load_dword v92, v73, s[2:3] offset:128
	global_store_dword v73, v53, s[28:29] offset:0
	s_waitcnt vmcnt(41)
	v_sub_f32_e32 v179, v93, v156
	v_mul_f32_e32 v179, v179, v157
	v_fma_f32 v179, v168, v179, v172
	v_cndmask_b32_e64 v93, v93, v179, s[98:99]
	v_mul_f32_e32 v54, v54, v77
	v_fmac_f32_e32 v54, 0x3fb504f3, v93
	global_load_dword v93, v74, s[2:3] offset:-3968
	global_store_dword v74, v54, s[28:29] offset:-4096
	s_waitcnt vmcnt(42)
	v_sub_f32_e32 v179, v94, v158
	v_mul_f32_e32 v179, v179, v159
	v_fma_f32 v179, v168, v179, v172
	v_cndmask_b32_e64 v94, v94, v179, s[98:99]
	v_mul_f32_e32 v55, v55, v77
	v_fmac_f32_e32 v55, 0x3fb504f3, v94
	global_load_dword v94, v74, s[2:3] offset:128
	global_store_dword v74, v55, s[28:29] offset:0
	s_waitcnt vmcnt(43)
	v_sub_f32_e32 v179, v95, v160
	v_mul_f32_e32 v179, v179, v161
	v_fma_f32 v179, v168, v179, v172
	v_cndmask_b32_e64 v95, v95, v179, s[98:99]
	v_mul_f32_e32 v48, v48, v77
	v_fmac_f32_e32 v48, 0x3fb504f3, v95
	global_load_dword v95, v75, s[2:3] offset:-3968
	global_store_dword v75, v48, s[28:29] offset:-4096
	s_waitcnt vmcnt(44)
	v_sub_f32_e32 v179, v96, v162
	v_mul_f32_e32 v179, v179, v163
	v_fma_f32 v179, v168, v179, v172
	v_cndmask_b32_e64 v96, v96, v179, s[98:99]
	v_mul_f32_e32 v49, v49, v77
	v_fmac_f32_e32 v49, 0x3fb504f3, v96
	global_load_dword v96, v75, s[2:3] offset:128
	global_store_dword v75, v49, s[28:29] offset:0
	s_waitcnt vmcnt(45)
	v_sub_f32_e32 v179, v97, v164
	v_mul_f32_e32 v179, v179, v165
	v_fma_f32 v179, v168, v179, v172
	v_cndmask_b32_e64 v97, v97, v179, s[98:99]
	v_mul_f32_e32 v50, v50, v77
	v_fmac_f32_e32 v50, 0x3fb504f3, v97
	global_load_dword v97, v76, s[2:3] offset:-3968
	global_store_dword v76, v50, s[28:29] offset:-4096
	s_waitcnt vmcnt(46)
	v_sub_f32_e32 v179, v98, v166
	v_mul_f32_e32 v179, v179, v167
	v_fma_f32 v179, v168, v179, v172
	v_cndmask_b32_e64 v98, v98, v179, s[98:99]
	v_mul_f32_e32 v51, v51, v77
	v_fmac_f32_e32 v51, 0x3fb504f3, v98
	global_load_dword v98, v76, s[2:3] offset:128
	global_store_dword v76, v51, s[28:29] offset:0
	s_waitcnt vmcnt(47)
	v_sub_f32_e32 v179, v99, v136
	v_mul_f32_e32 v179, v179, v137
	v_fma_f32 v179, v169, v179, v173
	v_cndmask_b32_e64 v99, v99, v179, s[98:99]
	v_mul_f32_e32 v44, v44, v78
	v_fmac_f32_e32 v44, 0x3fb504f3, v99
	global_load_dword v99, v69, s[2:3] offset:-3904
	global_store_dword v69, v44, s[28:29] offset:-4032
	s_waitcnt vmcnt(48)
	v_sub_f32_e32 v179, v100, v138
	v_mul_f32_e32 v179, v179, v139
	v_fma_f32 v179, v169, v179, v173
	v_cndmask_b32_e64 v100, v100, v179, s[98:99]
	v_mul_f32_e32 v45, v45, v78
	v_fmac_f32_e32 v45, 0x3fb504f3, v100
	global_load_dword v100, v69, s[2:3] offset:192
	global_store_dword v69, v45, s[28:29] offset:64
	s_waitcnt vmcnt(49)
	v_sub_f32_e32 v179, v101, v140
	v_mul_f32_e32 v179, v179, v141
	v_fma_f32 v179, v169, v179, v173
	v_cndmask_b32_e64 v101, v101, v179, s[98:99]
	v_mul_f32_e32 v46, v46, v78
	v_fmac_f32_e32 v46, 0x3fb504f3, v101
	global_load_dword v101, v70, s[2:3] offset:-3904
	global_store_dword v70, v46, s[28:29] offset:-4032
	s_waitcnt vmcnt(50)
	v_sub_f32_e32 v179, v102, v142
	v_mul_f32_e32 v179, v179, v143
	v_fma_f32 v179, v169, v179, v173
	v_cndmask_b32_e64 v102, v102, v179, s[98:99]
	v_mul_f32_e32 v47, v47, v78
	v_fmac_f32_e32 v47, 0x3fb504f3, v102
	global_load_dword v102, v70, s[2:3] offset:192
	global_store_dword v70, v47, s[28:29] offset:64
	s_waitcnt vmcnt(51)
	v_sub_f32_e32 v179, v103, v144
	v_mul_f32_e32 v179, v179, v145
	v_fma_f32 v179, v169, v179, v173
	v_cndmask_b32_e64 v103, v103, v179, s[98:99]
	v_mul_f32_e32 v40, v40, v78
	v_fmac_f32_e32 v40, 0x3fb504f3, v103
	global_load_dword v103, v71, s[2:3] offset:-3904
	global_store_dword v71, v40, s[28:29] offset:-4032
	s_waitcnt vmcnt(52)
	v_sub_f32_e32 v179, v104, v146
	v_mul_f32_e32 v179, v179, v147
	v_fma_f32 v179, v169, v179, v173
	v_cndmask_b32_e64 v104, v104, v179, s[98:99]
	v_mul_f32_e32 v41, v41, v78
	v_fmac_f32_e32 v41, 0x3fb504f3, v104
	global_load_dword v104, v71, s[2:3] offset:192
	global_store_dword v71, v41, s[28:29] offset:64
	s_waitcnt vmcnt(53)
	v_sub_f32_e32 v179, v105, v148
	v_mul_f32_e32 v179, v179, v149
	v_fma_f32 v179, v169, v179, v173
	v_cndmask_b32_e64 v105, v105, v179, s[98:99]
	v_mul_f32_e32 v42, v42, v78
	v_fmac_f32_e32 v42, 0x3fb504f3, v105
	global_load_dword v105, v72, s[2:3] offset:-3904
	global_store_dword v72, v42, s[28:29] offset:-4032
	s_waitcnt vmcnt(54)
	v_sub_f32_e32 v179, v106, v150
	v_mul_f32_e32 v179, v179, v151
	v_fma_f32 v179, v169, v179, v173
	v_cndmask_b32_e64 v106, v106, v179, s[98:99]
	v_mul_f32_e32 v43, v43, v78
	v_fmac_f32_e32 v43, 0x3fb504f3, v106
	global_load_dword v106, v72, s[2:3] offset:192
	global_store_dword v72, v43, s[28:29] offset:64
	s_waitcnt vmcnt(55)
	v_sub_f32_e32 v179, v107, v152
	v_mul_f32_e32 v179, v179, v153
	v_fma_f32 v179, v169, v179, v173
	v_cndmask_b32_e64 v107, v107, v179, s[98:99]
	v_mul_f32_e32 v36, v36, v78
	v_fmac_f32_e32 v36, 0x3fb504f3, v107
	global_load_dword v107, v73, s[2:3] offset:-3904
	global_store_dword v73, v36, s[28:29] offset:-4032
	s_waitcnt vmcnt(56)
	v_sub_f32_e32 v179, v108, v154
	v_mul_f32_e32 v179, v179, v155
	v_fma_f32 v179, v169, v179, v173
	v_cndmask_b32_e64 v108, v108, v179, s[98:99]
	v_mul_f32_e32 v37, v37, v78
	v_fmac_f32_e32 v37, 0x3fb504f3, v108
	global_load_dword v108, v73, s[2:3] offset:192
	global_store_dword v73, v37, s[28:29] offset:64
	s_waitcnt vmcnt(57)
	v_sub_f32_e32 v179, v109, v156
	v_mul_f32_e32 v179, v179, v157
	v_fma_f32 v179, v169, v179, v173
	v_cndmask_b32_e64 v109, v109, v179, s[98:99]
	v_mul_f32_e32 v38, v38, v78
	v_fmac_f32_e32 v38, 0x3fb504f3, v109
	global_load_dword v109, v74, s[2:3] offset:-3904
	global_store_dword v74, v38, s[28:29] offset:-4032
	s_waitcnt vmcnt(58)
	v_sub_f32_e32 v179, v110, v158
	v_mul_f32_e32 v179, v179, v159
	v_fma_f32 v179, v169, v179, v173
	v_cndmask_b32_e64 v110, v110, v179, s[98:99]
	v_mul_f32_e32 v39, v39, v78
	v_fmac_f32_e32 v39, 0x3fb504f3, v110
	global_load_dword v110, v74, s[2:3] offset:192
	global_store_dword v74, v39, s[28:29] offset:64
	s_waitcnt vmcnt(59)
	v_sub_f32_e32 v179, v111, v160
	v_mul_f32_e32 v179, v179, v161
	v_fma_f32 v179, v169, v179, v173
	v_cndmask_b32_e64 v111, v111, v179, s[98:99]
	v_mul_f32_e32 v32, v32, v78
	v_fmac_f32_e32 v32, 0x3fb504f3, v111
	global_load_dword v111, v75, s[2:3] offset:-3904
	global_store_dword v75, v32, s[28:29] offset:-4032
	s_waitcnt vmcnt(60)
	v_sub_f32_e32 v179, v112, v162
	v_mul_f32_e32 v179, v179, v163
	v_fma_f32 v179, v169, v179, v173
	v_cndmask_b32_e64 v112, v112, v179, s[98:99]
	v_mul_f32_e32 v33, v33, v78
	v_fmac_f32_e32 v33, 0x3fb504f3, v112
	global_load_dword v112, v75, s[2:3] offset:192
	global_store_dword v75, v33, s[28:29] offset:64
	s_waitcnt vmcnt(61)
	v_sub_f32_e32 v179, v116, v164
	v_mul_f32_e32 v179, v179, v165
	v_fma_f32 v179, v169, v179, v173
	v_cndmask_b32_e64 v116, v116, v179, s[98:99]
	v_mul_f32_e32 v34, v34, v78
	v_fmac_f32_e32 v34, 0x3fb504f3, v116
	global_load_dword v116, v76, s[2:3] offset:-3904
	global_store_dword v76, v34, s[28:29] offset:-4032
	s_waitcnt vmcnt(62)
	v_sub_f32_e32 v179, v117, v166
	v_mul_f32_e32 v179, v179, v167
	v_fma_f32 v179, v169, v179, v173
	v_cndmask_b32_e64 v117, v117, v179, s[98:99]
	v_mul_f32_e32 v35, v35, v78
	v_fmac_f32_e32 v35, 0x3fb504f3, v117
	global_load_dword v117, v76, s[2:3] offset:192
	global_store_dword v76, v35, s[28:29] offset:64
	s_waitcnt vmcnt(63)
	v_sub_f32_e32 v179, v81, v136
	v_mul_f32_e32 v179, v179, v137
	v_fma_f32 v179, v170, v179, v174
	v_cndmask_b32_e64 v81, v81, v179, s[98:99]
	v_mul_f32_e32 v28, v28, v79
	v_fmac_f32_e32 v28, 0x3fb504f3, v81
	global_store_dword v69, v28, s[28:29] offset:-3968
	s_waitcnt vmcnt(62)
	v_sub_f32_e32 v179, v82, v138
	v_mul_f32_e32 v179, v179, v139
	v_fma_f32 v179, v170, v179, v174
	v_cndmask_b32_e64 v82, v82, v179, s[98:99]
	v_mul_f32_e32 v29, v29, v79
	v_fmac_f32_e32 v29, 0x3fb504f3, v82
	global_store_dword v69, v29, s[28:29] offset:128
	s_waitcnt vmcnt(61)
	v_sub_f32_e32 v179, v83, v140
	v_mul_f32_e32 v179, v179, v141
	v_fma_f32 v179, v170, v179, v174
	v_cndmask_b32_e64 v83, v83, v179, s[98:99]
	v_mul_f32_e32 v30, v30, v79
	v_fmac_f32_e32 v30, 0x3fb504f3, v83
	global_store_dword v70, v30, s[28:29] offset:-3968
	s_waitcnt vmcnt(60)
	v_sub_f32_e32 v179, v84, v142
	v_mul_f32_e32 v179, v179, v143
	v_fma_f32 v179, v170, v179, v174
	v_cndmask_b32_e64 v84, v84, v179, s[98:99]
	v_mul_f32_e32 v31, v31, v79
	v_fmac_f32_e32 v31, 0x3fb504f3, v84
	global_store_dword v70, v31, s[28:29] offset:128
	s_waitcnt vmcnt(59)
	v_sub_f32_e32 v179, v85, v144
	v_mul_f32_e32 v179, v179, v145
	v_fma_f32 v179, v170, v179, v174
	v_cndmask_b32_e64 v85, v85, v179, s[98:99]
	v_mul_f32_e32 v24, v24, v79
	v_fmac_f32_e32 v24, 0x3fb504f3, v85
	global_store_dword v71, v24, s[28:29] offset:-3968
	s_waitcnt vmcnt(58)
	v_sub_f32_e32 v179, v86, v146
	v_mul_f32_e32 v179, v179, v147
	v_fma_f32 v179, v170, v179, v174
	v_cndmask_b32_e64 v86, v86, v179, s[98:99]
	v_mul_f32_e32 v25, v25, v79
	v_fmac_f32_e32 v25, 0x3fb504f3, v86
	global_store_dword v71, v25, s[28:29] offset:128
	s_waitcnt vmcnt(57)
	v_sub_f32_e32 v179, v87, v148
	v_mul_f32_e32 v179, v179, v149
	v_fma_f32 v179, v170, v179, v174
	v_cndmask_b32_e64 v87, v87, v179, s[98:99]
	v_mul_f32_e32 v26, v26, v79
	v_fmac_f32_e32 v26, 0x3fb504f3, v87
	global_store_dword v72, v26, s[28:29] offset:-3968
	s_waitcnt vmcnt(56)
	v_sub_f32_e32 v179, v89, v150
	v_mul_f32_e32 v179, v179, v151
	v_fma_f32 v179, v170, v179, v174
	v_cndmask_b32_e64 v89, v89, v179, s[98:99]
	v_mul_f32_e32 v27, v27, v79
	v_fmac_f32_e32 v27, 0x3fb504f3, v89
	global_store_dword v72, v27, s[28:29] offset:128
	s_waitcnt vmcnt(55)
	v_sub_f32_e32 v179, v91, v152
	v_mul_f32_e32 v179, v179, v153
	v_fma_f32 v179, v170, v179, v174
	v_cndmask_b32_e64 v91, v91, v179, s[98:99]
	v_mul_f32_e32 v20, v20, v79
	v_fmac_f32_e32 v20, 0x3fb504f3, v91
	global_store_dword v73, v20, s[28:29] offset:-3968
	s_waitcnt vmcnt(54)
	v_sub_f32_e32 v179, v92, v154
	v_mul_f32_e32 v179, v179, v155
	v_fma_f32 v179, v170, v179, v174
	v_cndmask_b32_e64 v92, v92, v179, s[98:99]
	v_mul_f32_e32 v21, v21, v79
	v_fmac_f32_e32 v21, 0x3fb504f3, v92
	global_store_dword v73, v21, s[28:29] offset:128
	s_waitcnt vmcnt(53)
	v_sub_f32_e32 v179, v93, v156
	v_mul_f32_e32 v179, v179, v157
	v_fma_f32 v179, v170, v179, v174
	v_cndmask_b32_e64 v93, v93, v179, s[98:99]
	v_mul_f32_e32 v22, v22, v79
	v_fmac_f32_e32 v22, 0x3fb504f3, v93
	global_store_dword v74, v22, s[28:29] offset:-3968
	s_waitcnt vmcnt(52)
	v_sub_f32_e32 v179, v94, v158
	v_mul_f32_e32 v179, v179, v159
	v_fma_f32 v179, v170, v179, v174
	v_cndmask_b32_e64 v94, v94, v179, s[98:99]
	v_mul_f32_e32 v23, v23, v79
	v_fmac_f32_e32 v23, 0x3fb504f3, v94
	global_store_dword v74, v23, s[28:29] offset:128
	s_waitcnt vmcnt(51)
	v_sub_f32_e32 v179, v95, v160
	v_mul_f32_e32 v179, v179, v161
	v_fma_f32 v179, v170, v179, v174
	v_cndmask_b32_e64 v95, v95, v179, s[98:99]
	v_mul_f32_e32 v16, v16, v79
	v_fmac_f32_e32 v16, 0x3fb504f3, v95
	global_store_dword v75, v16, s[28:29] offset:-3968
	s_waitcnt vmcnt(50)
	v_sub_f32_e32 v179, v96, v162
	v_mul_f32_e32 v179, v179, v163
	v_fma_f32 v179, v170, v179, v174
	v_cndmask_b32_e64 v96, v96, v179, s[98:99]
	v_mul_f32_e32 v17, v17, v79
	v_fmac_f32_e32 v17, 0x3fb504f3, v96
	global_store_dword v75, v17, s[28:29] offset:128
	s_waitcnt vmcnt(49)
	v_sub_f32_e32 v179, v97, v164
	v_mul_f32_e32 v179, v179, v165
	v_fma_f32 v179, v170, v179, v174
	v_cndmask_b32_e64 v97, v97, v179, s[98:99]
	v_mul_f32_e32 v18, v18, v79
	v_fmac_f32_e32 v18, 0x3fb504f3, v97
	global_store_dword v76, v18, s[28:29] offset:-3968
	s_waitcnt vmcnt(48)
	v_sub_f32_e32 v179, v98, v166
	v_mul_f32_e32 v179, v179, v167
	v_fma_f32 v179, v170, v179, v174
	v_cndmask_b32_e64 v98, v98, v179, s[98:99]
	v_mul_f32_e32 v19, v19, v79
	v_fmac_f32_e32 v19, 0x3fb504f3, v98
	global_store_dword v76, v19, s[28:29] offset:128
	s_waitcnt vmcnt(47)
	v_sub_f32_e32 v179, v99, v136
	v_mul_f32_e32 v179, v179, v137
	v_fma_f32 v179, v171, v179, v175
	v_cndmask_b32_e64 v99, v99, v179, s[98:99]
	v_mul_f32_e32 v12, v12, v80
	v_fmac_f32_e32 v12, 0x3fb504f3, v99
	global_store_dword v69, v12, s[28:29] offset:-3904
	s_waitcnt vmcnt(46)
	v_sub_f32_e32 v179, v100, v138
	v_mul_f32_e32 v179, v179, v139
	v_fma_f32 v179, v171, v179, v175
	v_cndmask_b32_e64 v100, v100, v179, s[98:99]
	v_mul_f32_e32 v13, v13, v80
	v_fmac_f32_e32 v13, 0x3fb504f3, v100
	global_store_dword v69, v13, s[28:29] offset:192
	s_waitcnt vmcnt(45)
	v_sub_f32_e32 v179, v101, v140
	v_mul_f32_e32 v179, v179, v141
	v_fma_f32 v179, v171, v179, v175
	v_cndmask_b32_e64 v101, v101, v179, s[98:99]
	v_mul_f32_e32 v14, v14, v80
	v_fmac_f32_e32 v14, 0x3fb504f3, v101
	global_store_dword v70, v14, s[28:29] offset:-3904
	s_waitcnt vmcnt(44)
	v_sub_f32_e32 v179, v102, v142
	v_mul_f32_e32 v179, v179, v143
	v_fma_f32 v179, v171, v179, v175
	v_cndmask_b32_e64 v102, v102, v179, s[98:99]
	v_mul_f32_e32 v15, v15, v80
	v_fmac_f32_e32 v15, 0x3fb504f3, v102
	global_store_dword v70, v15, s[28:29] offset:192
	s_waitcnt vmcnt(43)
	v_sub_f32_e32 v179, v103, v144
	v_mul_f32_e32 v179, v179, v145
	v_fma_f32 v179, v171, v179, v175
	v_cndmask_b32_e64 v103, v103, v179, s[98:99]
	v_mul_f32_e32 v8, v8, v80
	v_fmac_f32_e32 v8, 0x3fb504f3, v103
	global_store_dword v71, v8, s[28:29] offset:-3904
	s_waitcnt vmcnt(42)
	v_sub_f32_e32 v179, v104, v146
	v_mul_f32_e32 v179, v179, v147
	v_fma_f32 v179, v171, v179, v175
	v_cndmask_b32_e64 v104, v104, v179, s[98:99]
	v_mul_f32_e32 v9, v9, v80
	v_fmac_f32_e32 v9, 0x3fb504f3, v104
	global_store_dword v71, v9, s[28:29] offset:192
	s_waitcnt vmcnt(41)
	v_sub_f32_e32 v179, v105, v148
	v_mul_f32_e32 v179, v179, v149
	v_fma_f32 v179, v171, v179, v175
	v_cndmask_b32_e64 v105, v105, v179, s[98:99]
	v_mul_f32_e32 v10, v10, v80
	v_fmac_f32_e32 v10, 0x3fb504f3, v105
	global_store_dword v72, v10, s[28:29] offset:-3904
	s_waitcnt vmcnt(40)
	v_sub_f32_e32 v179, v106, v150
	v_mul_f32_e32 v179, v179, v151
	v_fma_f32 v179, v171, v179, v175
	v_cndmask_b32_e64 v106, v106, v179, s[98:99]
	v_mul_f32_e32 v11, v11, v80
	v_fmac_f32_e32 v11, 0x3fb504f3, v106
	global_store_dword v72, v11, s[28:29] offset:192
	s_waitcnt vmcnt(39)
	v_sub_f32_e32 v179, v107, v152
	v_mul_f32_e32 v179, v179, v153
	v_fma_f32 v179, v171, v179, v175
	v_cndmask_b32_e64 v107, v107, v179, s[98:99]
	v_mul_f32_e32 v4, v4, v80
	v_fmac_f32_e32 v4, 0x3fb504f3, v107
	global_store_dword v73, v4, s[28:29] offset:-3904
	s_waitcnt vmcnt(38)
	v_sub_f32_e32 v179, v108, v154
	v_mul_f32_e32 v179, v179, v155
	v_fma_f32 v179, v171, v179, v175
	v_cndmask_b32_e64 v108, v108, v179, s[98:99]
	v_mul_f32_e32 v5, v5, v80
	v_fmac_f32_e32 v5, 0x3fb504f3, v108
	global_store_dword v73, v5, s[28:29] offset:192
	s_waitcnt vmcnt(37)
	v_sub_f32_e32 v179, v109, v156
	v_mul_f32_e32 v179, v179, v157
	v_fma_f32 v179, v171, v179, v175
	v_cndmask_b32_e64 v109, v109, v179, s[98:99]
	v_mul_f32_e32 v6, v6, v80
	v_fmac_f32_e32 v6, 0x3fb504f3, v109
	global_store_dword v74, v6, s[28:29] offset:-3904
	s_waitcnt vmcnt(36)
	v_sub_f32_e32 v179, v110, v158
	v_mul_f32_e32 v179, v179, v159
	v_fma_f32 v179, v171, v179, v175
	v_cndmask_b32_e64 v110, v110, v179, s[98:99]
	v_mul_f32_e32 v7, v7, v80
	v_fmac_f32_e32 v7, 0x3fb504f3, v110
	global_store_dword v74, v7, s[28:29] offset:192
	s_waitcnt vmcnt(35)
	v_sub_f32_e32 v179, v111, v160
	v_mul_f32_e32 v179, v179, v161
	v_fma_f32 v179, v171, v179, v175
	v_cndmask_b32_e64 v111, v111, v179, s[98:99]
	v_mul_f32_e32 v0, v0, v80
	v_fmac_f32_e32 v0, 0x3fb504f3, v111
	global_store_dword v75, v0, s[28:29] offset:-3904
	s_waitcnt vmcnt(34)
	v_sub_f32_e32 v179, v112, v162
	v_mul_f32_e32 v179, v179, v163
	v_fma_f32 v179, v171, v179, v175
	v_cndmask_b32_e64 v112, v112, v179, s[98:99]
	v_mul_f32_e32 v1, v1, v80
	v_fmac_f32_e32 v1, 0x3fb504f3, v112
	global_store_dword v75, v1, s[28:29] offset:192
	s_waitcnt vmcnt(33)
	v_sub_f32_e32 v179, v116, v164
	v_mul_f32_e32 v179, v179, v165
	v_fma_f32 v179, v171, v179, v175
	v_cndmask_b32_e64 v116, v116, v179, s[98:99]
	v_mul_f32_e32 v2, v2, v80
	v_fmac_f32_e32 v2, 0x3fb504f3, v116
	global_store_dword v76, v2, s[28:29] offset:-3904
	s_waitcnt vmcnt(32)
	v_sub_f32_e32 v179, v117, v166
	v_mul_f32_e32 v179, v179, v167
	v_fma_f32 v179, v171, v179, v175
	v_cndmask_b32_e64 v117, v117, v179, s[98:99]
	v_mul_f32_e32 v3, v3, v80
	v_fmac_f32_e32 v3, 0x3fb504f3, v117
	global_store_dword v76, v3, s[28:29] offset:192
	s_cbranch_scc0 .LBB0_153

.LBB0_172:
	s_or_b64 exec, exec, s[10:11]
	global_load_dwordx4 v[48:51], v[90:91], off offset:-2048
	global_load_dwordx4 v[52:55], v[90:91], off offset:-1024
	global_load_dwordx4 v[56:59], v[90:91], off
	global_load_dwordx4 v[60:63], v[90:91], off offset:1024
	s_waitcnt vmcnt(3)
	v_add_f32_e32 v65, 0, v48
	v_add_f32_e32 v65, v65, v49
	v_add_f32_e32 v65, v65, v50
	v_add_f32_e32 v65, v65, v51
	s_waitcnt vmcnt(2)
	v_add_f32_e32 v65, v65, v52
	v_add_f32_e32 v65, v65, v53
	v_add_f32_e32 v65, v65, v54
	v_add_f32_e32 v65, v65, v55
	s_waitcnt vmcnt(1)
	v_add_f32_e32 v65, v65, v56
	v_add_f32_e32 v65, v65, v57
	v_add_f32_e32 v65, v65, v58
	v_add_f32_e32 v65, v65, v59
	s_waitcnt vmcnt(0)
	v_add_f32_e32 v65, v65, v60
	v_add_f32_e32 v65, v65, v61
	v_add_f32_e32 v65, v65, v62
	v_add_f32_e32 v65, v65, v63
	ds_bpermute_b32 v67, v109, v65
	s_waitcnt lgkmcnt(0)
	v_add_f32_e32 v65, v65, v67
	ds_bpermute_b32 v67, v110, v65
	s_waitcnt lgkmcnt(0)
	v_add_f32_e32 v65, v65, v67
	ds_bpermute_b32 v67, v111, v65
	s_waitcnt lgkmcnt(0)
	v_add_f32_e32 v65, v65, v67
	ds_bpermute_b32 v67, v115, v65
	s_waitcnt lgkmcnt(0)
	v_add_f32_e32 v65, v65, v67
	ds_bpermute_b32 v67, v116, v65
	s_waitcnt lgkmcnt(0)
	v_add_f32_e32 v65, v65, v67
	ds_bpermute_b32 v67, v117, v65
	s_waitcnt lgkmcnt(0)
	v_add_f32_e32 v65, v65, v67
	v_mul_f32_e32 v120, 0x3a800000, v65
	v_mov_b32_e32 v252, v120
	v_pk_add_f32 v[48:49], v[48:49], v[120:121] op_sel_hi:[1,0] neg_lo:[0,1] neg_hi:[0,1]
	v_pk_add_f32 v[50:51], v[50:51], v[120:121] op_sel_hi:[1,0] neg_lo:[0,1] neg_hi:[0,1]
	v_pk_add_f32 v[52:53], v[52:53], v[120:121] op_sel_hi:[1,0] neg_lo:[0,1] neg_hi:[0,1]
	v_pk_add_f32 v[54:55], v[54:55], v[120:121] op_sel_hi:[1,0] neg_lo:[0,1] neg_hi:[0,1]
	v_pk_add_f32 v[56:57], v[56:57], v[120:121] op_sel_hi:[1,0] neg_lo:[0,1] neg_hi:[0,1]
	v_pk_add_f32 v[58:59], v[58:59], v[120:121] op_sel_hi:[1,0] neg_lo:[0,1] neg_hi:[0,1]
	v_pk_add_f32 v[60:61], v[60:61], v[120:121] op_sel_hi:[1,0] neg_lo:[0,1] neg_hi:[0,1]
	v_pk_add_f32 v[62:63], v[62:63], v[120:121] op_sel_hi:[1,0] neg_lo:[0,1] neg_hi:[0,1]
	v_pk_mul_f32 v[120:121], v[48:49], v[48:49]
	v_pk_mul_f32 v[122:123], v[50:51], v[50:51]
	v_add_f32_e32 v65, v120, v121
	v_add_f32_e32 v65, v122, v65
	v_pk_mul_f32 v[124:125], v[52:53], v[52:53]
	v_add_f32_e32 v65, v123, v65
	v_add_f32_e32 v65, v124, v65
	v_pk_mul_f32 v[126:127], v[54:55], v[54:55]
	v_add_f32_e32 v65, v125, v65
	v_add_f32_e32 v65, v126, v65
	v_pk_mul_f32 v[128:129], v[56:57], v[56:57]
	v_add_f32_e32 v65, v127, v65
	v_add_f32_e32 v65, v128, v65
	v_pk_mul_f32 v[130:131], v[58:59], v[58:59]
	v_add_f32_e32 v65, v129, v65
	v_add_f32_e32 v65, v130, v65
	v_pk_mul_f32 v[132:133], v[60:61], v[60:61]
	v_add_f32_e32 v65, v131, v65
	v_add_f32_e32 v65, v132, v65
	v_pk_mul_f32 v[134:135], v[62:63], v[62:63]
	v_add_f32_e32 v65, v133, v65
	v_add_f32_e32 v65, v134, v65
	v_add_f32_e32 v65, v135, v65
	ds_bpermute_b32 v67, v109, v65
	s_waitcnt lgkmcnt(0)
	v_add_f32_e32 v65, v65, v67
	ds_bpermute_b32 v67, v110, v65
	s_waitcnt lgkmcnt(0)
	v_add_f32_e32 v65, v65, v67
	ds_bpermute_b32 v67, v111, v65
	s_waitcnt lgkmcnt(0)
	v_add_f32_e32 v65, v65, v67
	ds_bpermute_b32 v67, v115, v65
	s_waitcnt lgkmcnt(0)
	v_add_f32_e32 v65, v65, v67
	ds_bpermute_b32 v67, v116, v65
	s_waitcnt lgkmcnt(0)
	v_add_f32_e32 v65, v65, v67
	ds_bpermute_b32 v67, v117, v65
	s_waitcnt lgkmcnt(0)
	v_add_f32_e32 v65, v65, v67
	v_fmamk_f32 v65, v65, 0x3a800000, v184
	v_mul_f32_e32 v67, 0x4b800000, v65
	v_cmp_gt_f32_e32 vcc, s49, v65
	s_nop 1
	v_cndmask_b32_e32 v65, v65, v67, vcc
	v_rsq_f32_e32 v67, v65
	v_ashrrev_i32_e32 v65, 8, v66
	v_mul_f32_e32 v119, 0x45800000, v67
	v_cndmask_b32_e32 v120, v67, v119, vcc
	v_mov_b32_e32 v253, v120
	v_lshlrev_b32_e32 v254, 3, v66
	v_add_u32_e32 v254, 0x1e200000, v254
	s_mov_b64 exec, 1
	global_store_dwordx2 v254, v[252:253], s[30:31]
	s_mov_b64 exec, -1
	v_pk_mul_f32 v[48:49], v[48:49], v[120:121] op_sel_hi:[1,0]
	v_pk_mul_f32 v[50:51], v[50:51], v[120:121] op_sel_hi:[1,0]
	v_pk_mul_f32 v[52:53], v[52:53], v[120:121] op_sel_hi:[1,0]
	v_pk_mul_f32 v[54:55], v[54:55], v[120:121] op_sel_hi:[1,0]
	v_pk_mul_f32 v[122:123], v[56:57], v[120:121] op_sel_hi:[1,0]
	v_pk_mul_f32 v[124:125], v[58:59], v[120:121] op_sel_hi:[1,0]
	v_pk_mul_f32 v[126:127], v[60:61], v[120:121] op_sel_hi:[1,0]
	v_pk_mul_f32 v[120:121], v[62:63], v[120:121] op_sel_hi:[1,0]
	v_pk_fma_f32 v[60:61], v[0:1], v[48:49], v[8:9]
	v_pk_fma_f32 v[62:63], v[2:3], v[50:51], v[10:11]
	v_pk_fma_f32 v[56:57], v[4:5], v[52:53], v[12:13]
	v_pk_fma_f32 v[58:59], v[6:7], v[54:55], v[14:15]
	v_pk_fma_f32 v[52:53], v[16:17], v[122:123], v[24:25]
	v_pk_fma_f32 v[54:55], v[18:19], v[124:125], v[26:27]
	v_pk_fma_f32 v[48:49], v[20:21], v[126:127], v[28:29]
	v_pk_fma_f32 v[50:51], v[22:23], v[120:121], v[30:31]
	v_cmp_ne_u32_e32 vcc, v65, v112
	s_and_saveexec_b64 s[10:11], vcc
	s_cbranch_execz .LBB0_169
	v_cmp_lt_i32_e32 vcc, -1, v112
	s_and_saveexec_b64 s[12:13], vcc
	s_cbranch_execz .LBB0_168
	v_lshlrev_b64 v[120:121], 12, v[112:113]
	v_lshl_add_u64 v[120:121], v[84:85], 0, v[120:121]
	global_atomic_add_f32 v[120:121], v80, off
	global_atomic_add_f32 v[120:121], v81, off offset:4
	global_atomic_add_f32 v[120:121], v82, off offset:8
	global_atomic_add_f32 v[120:121], v83, off offset:12
	global_atomic_add_f32 v[120:121], v78, off offset:1024
	global_atomic_add_f32 v[120:121], v79, off offset:1028
	global_atomic_add_f32 v[120:121], v76, off offset:1032
	global_atomic_add_f32 v[120:121], v77, off offset:1036
	global_atomic_add_f32 v[120:121], v74, off offset:2048
	global_atomic_add_f32 v[120:121], v75, off offset:2052
	global_atomic_add_f32 v[120:121], v72, off offset:2056
	global_atomic_add_f32 v[120:121], v73, off offset:2060
	global_atomic_add_f32 v[120:121], v70, off offset:3072
	global_atomic_add_f32 v[120:121], v71, off offset:3076
	global_atomic_add_f32 v[120:121], v68, off offset:3080
	global_atomic_add_f32 v[120:121], v69, off offset:3084
	v_mov_b32_e32 v81, 0
	v_mov_b32_e32 v80, v81
	v_mov_b32_e32 v83, v81
	v_mov_b32_e32 v82, v81
	v_mov_b32_e32 v79, v81
	v_mov_b32_e32 v78, v81
	v_mov_b32_e32 v77, v81
	v_mov_b32_e32 v76, v81
	v_mov_b32_e32 v75, v81
	v_mov_b32_e32 v74, v81
	v_mov_b32_e32 v73, v81
	v_mov_b32_e32 v72, v81
	v_mov_b32_e32 v71, v81
	v_mov_b32_e32 v70, v81
	v_mov_b32_e32 v69, v81
	v_mov_b32_e32 v68, v81
	s_branch .LBB0_168

.LBB0_601:
	s_add_i32 s4, s13, 0xffff8000
	v_mov_b32_e32 v64, v182
	s_waitcnt vmcnt(0)
	s_waitcnt vmcnt(0) lgkmcnt(0)
	s_barrier
	s_and_b32 s14, s13, 0x8000
	s_and_b32 s15, s4, 0x8000
	v_or_b32_e32 v71, s15, v86
	v_lshrrev_b32_e32 v65, 4, v64
	v_ashrrev_i32_e32 v66, 3, v64
	v_add_u32_e32 v68, 0x100, v64
	v_lshl_add_u32 v67, v64, 4, s14
	v_add_u32_e32 v69, 0x200, v64
	v_add_u32_e32 v72, s0, v66
	v_bitop3_b32 v65, v65, 7, v64 bitop3:0x48
	v_ashrrev_i32_e32 v73, 3, v68
	s_add_u32 s8, s30, s2
	v_add_u32_e32 v70, 0x300, v64
	v_readfirstlane_b32 s16, v67
	v_lshl_add_u32 v74, v68, 4, s14
	v_ashrrev_i32_e32 v75, 3, v69
	v_add_u32_e32 v64, s12, v66
	v_add_u32_e32 v68, 0x4000, v67
	v_add3_u32 v91, v71, v87, v88
	v_add3_u32 v80, v71, v89, v88
	v_mad_i64_i32 v[66:67], s[4:5], v72, s63, 0
	v_lshlrev_b32_e32 v81, 4, v65
	v_add_u32_e32 v71, s0, v73
	s_addc_u32 s9, s31, s3
	v_ashrrev_i32_e32 v76, 3, v70
	v_lshl_add_u32 v77, v70, 4, s14
	v_readfirstlane_b32 s17, v74
	v_add_u32_e32 v78, s0, v75
	v_readfirstlane_b32 s20, v68
	v_add_u32_e32 v68, s12, v73
	v_add_u32_e32 v73, 0x4000, v74
	v_add_u32_e32 v70, s12, v75
	v_or_b32_e32 v66, v66, v81
	v_mad_i64_i32 v[74:75], s[4:5], v71, s63, 0
	v_add_u32_e32 v79, s0, v76
	v_readfirstlane_b32 s19, v77
	v_add_u32_e32 v72, s12, v76
	v_add_u32_e32 v83, 0x4000, v77
	v_mad_i64_i32 v[76:77], s[4:5], v78, s63, 0
	v_lshl_add_u64 v[66:67], s[8:9], 0, v[66:67]
	v_or_b32_e32 v74, v74, v81
	v_lshl_add_u32 v69, v69, 4, s14
	v_ashrrev_i32_e32 v65, 31, v64
	v_mad_i64_i32 v[78:79], s[4:5], v79, s63, 0
	v_or_b32_e32 v76, v76, v81
	v_lshl_add_u64 v[66:67], v[66:67], 0, s[80:81]
	v_lshl_add_u64 v[74:75], s[8:9], 0, v[74:75]
	s_mov_b32 m0, s16
	v_readfirstlane_b32 s18, v69
	v_add_u32_e32 v82, 0x4000, v69
	v_lshlrev_b64 v[64:65], 11, v[64:65]
	v_ashrrev_i32_e32 v69, 31, v68
	v_or_b32_e32 v78, v78, v81
	v_lshl_add_u64 v[76:77], s[8:9], 0, v[76:77]
	global_load_lds_dwordx4 v[66:67], off
	v_lshl_add_u64 v[66:67], v[74:75], 0, s[80:81]
	s_mov_b32 m0, s17
	v_ashrrev_i32_e32 v71, 31, v70
	v_or_b32_e32 v64, v64, v81
	v_lshlrev_b64 v[68:69], 11, v[68:69]
	v_lshl_add_u64 v[78:79], s[8:9], 0, v[78:79]
	v_lshl_add_u64 v[74:75], v[76:77], 0, s[80:81]
	global_load_lds_dwordx4 v[66:67], off
	s_mov_b32 m0, s18
	v_readfirstlane_b32 s4, v73
	v_ashrrev_i32_e32 v73, 31, v72
	v_lshlrev_b64 v[70:71], 11, v[70:71]
	v_lshl_add_u64 v[64:65], s[8:9], 0, v[64:65]
	v_or_b32_e32 v68, v68, v81
	v_lshl_add_u64 v[76:77], v[78:79], 0, s[80:81]
	global_load_lds_dwordx4 v[74:75], off
	s_mov_b32 m0, s19
	v_lshlrev_b64 v[72:73], 11, v[72:73]
	v_or_b32_e32 v70, v70, v81
	v_lshl_add_u64 v[64:65], v[64:65], 0, s[82:83]
	v_lshl_add_u64 v[68:69], s[8:9], 0, v[68:69]
	global_load_lds_dwordx4 v[76:77], off
	s_mov_b32 m0, s20
	v_readfirstlane_b32 s5, v82
	v_or_b32_e32 v72, v72, v81
	v_lshl_add_u64 v[70:71], s[8:9], 0, v[70:71]
	v_lshl_add_u64 v[66:67], v[68:69], 0, s[82:83]
	global_load_lds_dwordx4 v[64:65], off
	s_mov_b32 m0, s4
	v_readfirstlane_b32 s21, v83
	v_lshl_add_u64 v[72:73], s[8:9], 0, v[72:73]
	v_lshl_add_u64 v[68:69], v[70:71], 0, s[82:83]
	global_load_lds_dwordx4 v[66:67], off
	s_mov_b32 m0, s5
	v_lshl_add_u64 v[70:71], v[72:73], 0, s[82:83]
	global_load_lds_dwordx4 v[68:69], off
	s_mov_b32 m0, s21
	s_add_u32 s2, s2, 0x80
	global_load_lds_dwordx4 v[70:71], off
	ds_read_b128 v[64:67], v91
	ds_read_b128 v[68:71], v80 offset:16384
	ds_read_b128 v[72:75], v80 offset:18432
	ds_read_b128 v[76:79], v80 offset:20480
	ds_read_b128 v[80:83], v80 offset:22528
	s_waitcnt lgkmcnt(0)
	v_mfma_f32_16x16x32_f16 v[60:63], v[64:67], v[68:71], v[60:63]
	s_addc_u32 s3, s3, 0
	s_add_i32 s13, s13, 0x8000
	s_cmpk_eq_i32 s2, 0x780
	v_mfma_f32_16x16x32_f16 v[56:59], v[64:67], v[72:75], v[56:59]
	v_mfma_f32_16x16x32_f16 v[52:55], v[64:67], v[76:79], v[52:55]
	v_mfma_f32_16x16x32_f16 v[48:51], v[64:67], v[80:83], v[48:51]
	ds_read_b128 v[64:67], v91 offset:2048
	s_waitcnt lgkmcnt(0)
	v_mfma_f32_16x16x32_f16 v[44:47], v[64:67], v[68:71], v[44:47]
	v_mfma_f32_16x16x32_f16 v[40:43], v[64:67], v[72:75], v[40:43]
	v_mfma_f32_16x16x32_f16 v[36:39], v[64:67], v[76:79], v[36:39]
	v_mfma_f32_16x16x32_f16 v[32:35], v[64:67], v[80:83], v[32:35]
	ds_read_b128 v[64:67], v91 offset:4096
	s_waitcnt lgkmcnt(0)
	v_mfma_f32_16x16x32_f16 v[24:27], v[64:67], v[68:71], v[24:27]
	v_mfma_f32_16x16x32_f16 v[20:23], v[64:67], v[72:75], v[20:23]
	v_mfma_f32_16x16x32_f16 v[16:19], v[64:67], v[76:79], v[16:19]
	v_mfma_f32_16x16x32_f16 v[12:15], v[64:67], v[80:83], v[12:15]
	ds_read_b128 v[64:67], v91 offset:6144
	s_waitcnt lgkmcnt(0)
	v_mfma_f32_16x16x32_f16 v[8:11], v[64:67], v[68:71], v[8:11]
	v_or_b32_e32 v68, s15, v90
	v_add3_u32 v91, v68, v87, v88
	v_add3_u32 v92, v68, v89, v88
	ds_read_b128 v[68:71], v91
	v_mfma_f32_16x16x32_f16 v[4:7], v[64:67], v[72:75], v[4:7]
	ds_read_b128 v[72:75], v92 offset:18432
	v_mfma_f32_16x16x32_f16 v[0:3], v[64:67], v[76:79], v[0:3]
	ds_read_b128 v[76:79], v92 offset:20480
	v_mfma_f32_16x16x32_f16 v[28:31], v[64:67], v[80:83], v[28:31]
	ds_read_b128 v[64:67], v92 offset:16384
	ds_read_b128 v[80:83], v92 offset:22528
	s_waitcnt lgkmcnt(1)
	v_mfma_f32_16x16x32_f16 v[60:63], v[68:71], v[64:67], v[60:63]
	v_mfma_f32_16x16x32_f16 v[56:59], v[68:71], v[72:75], v[56:59]
	v_mfma_f32_16x16x32_f16 v[52:55], v[68:71], v[76:79], v[52:55]
	s_waitcnt lgkmcnt(0)
	v_mfma_f32_16x16x32_f16 v[48:51], v[68:71], v[80:83], v[48:51]
	ds_read_b128 v[68:71], v91 offset:2048
	s_waitcnt lgkmcnt(0)
	v_mfma_f32_16x16x32_f16 v[44:47], v[68:71], v[64:67], v[44:47]
	v_mfma_f32_16x16x32_f16 v[40:43], v[68:71], v[72:75], v[40:43]
	v_mfma_f32_16x16x32_f16 v[36:39], v[68:71], v[76:79], v[36:39]
	v_mfma_f32_16x16x32_f16 v[32:35], v[68:71], v[80:83], v[32:35]
	ds_read_b128 v[68:71], v91 offset:4096
	s_waitcnt lgkmcnt(0)
	v_mfma_f32_16x16x32_f16 v[24:27], v[68:71], v[64:67], v[24:27]
	v_mfma_f32_16x16x32_f16 v[20:23], v[68:71], v[72:75], v[20:23]
	v_mfma_f32_16x16x32_f16 v[16:19], v[68:71], v[76:79], v[16:19]
	v_mfma_f32_16x16x32_f16 v[12:15], v[68:71], v[80:83], v[12:15]
	ds_read_b128 v[68:71], v91 offset:6144
	s_waitcnt lgkmcnt(0)
	v_mfma_f32_16x16x32_f16 v[8:11], v[68:71], v[64:67], v[8:11]
	v_mfma_f32_16x16x32_f16 v[4:7], v[68:71], v[72:75], v[4:7]
	v_mfma_f32_16x16x32_f16 v[0:3], v[68:71], v[76:79], v[0:3]
	v_mfma_f32_16x16x32_f16 v[28:31], v[68:71], v[80:83], v[28:31]
	s_cbranch_scc0 .LBB0_601
	v_add_u32_e32 v80, s14, v86
	v_add3_u32 v76, v80, v87, v88
	v_add3_u32 v91, v80, v89, v88
	s_waitcnt vmcnt(0)
	s_barrier
	ds_read_b128 v[64:67], v76
	ds_read_b128 v[68:71], v76 offset:2048
	ds_read_b128 v[72:75], v76 offset:4096
	ds_read_b128 v[76:79], v76 offset:6144
	ds_read_b128 v[80:83], v91 offset:16384
	ds_read_b128 v[92:95], v91 offset:18432
	ds_read_b128 v[96:99], v91 offset:20480
	ds_read_b128 v[100:103], v91 offset:22528
	s_waitcnt lgkmcnt(3)
	v_mfma_f32_16x16x32_f16 v[60:63], v[64:67], v[80:83], v[60:63]
	s_ashr_i32 s2, s0, 31
	s_lshr_b32 s2, s2, 19
	s_add_i32 s2, s0, s2
	s_waitcnt lgkmcnt(2)
	v_mfma_f32_16x16x32_f16 v[56:59], v[64:67], v[92:95], v[56:59]
	s_ashr_i32 s2, s2, 13
	s_add_i32 s2, s2, s10
	s_mul_hi_i32 s3, s2, 0x9000
	s_waitcnt lgkmcnt(1)
	v_mfma_f32_16x16x32_f16 v[52:55], v[64:67], v[96:99], v[52:55]
	s_mul_i32 s2, s2, 0x9000
	s_add_u32 s2, s50, s2
	s_addc_u32 s3, s51, s3
	s_waitcnt lgkmcnt(0)
	v_mfma_f32_16x16x32_f16 v[48:51], v[64:67], v[100:103], v[48:51]
	s_add_i32 s11, s11, s59
	s_cmpk_gt_i32 s11, 0x7ff
	v_mfma_f32_16x16x32_f16 v[64:67], v[68:71], v[80:83], v[44:47]
	v_mfma_f32_16x16x32_f16 v[40:43], v[68:71], v[92:95], v[40:43]
	v_mfma_f32_16x16x32_f16 v[36:39], v[68:71], v[96:99], v[36:39]
	v_mfma_f32_16x16x32_f16 v[32:35], v[68:71], v[100:103], v[32:35]
	v_mfma_f32_16x16x32_f16 v[68:71], v[72:75], v[80:83], v[24:27]
	v_mfma_f32_16x16x32_f16 v[20:23], v[72:75], v[92:95], v[20:23]
	v_mfma_f32_16x16x32_f16 v[16:19], v[72:75], v[96:99], v[16:19]
	v_mfma_f32_16x16x32_f16 v[72:75], v[72:75], v[100:103], v[12:15]
	s_nop 2
	v_add_u32_e32 v12, s14, v90
	v_add3_u32 v13, v12, v87, v88
	v_add3_u32 v12, v12, v89, v88
	v_mfma_f32_16x16x32_f16 v[80:83], v[76:79], v[80:83], v[8:11]
	v_mfma_f32_16x16x32_f16 v[92:95], v[76:79], v[92:95], v[4:7]
	v_mfma_f32_16x16x32_f16 v[0:3], v[76:79], v[96:99], v[0:3]
	v_mfma_f32_16x16x32_f16 v[76:79], v[76:79], v[100:103], v[28:31]
	s_nop 0
	ds_read_b128 v[4:7], v13
	ds_read_b128 v[8:11], v13 offset:2048
	ds_read_b128 v[96:99], v13 offset:4096
	ds_read_b128 v[100:103], v13 offset:6144
	ds_read_b128 v[104:107], v12 offset:16384
	ds_read_b128 v[108:111], v12 offset:18432
	ds_read_b128 v[116:119], v12 offset:20480
	ds_read_b128 v[120:123], v12 offset:22528
	s_waitcnt lgkmcnt(1)
	v_mfma_f32_16x16x32_f16 v[28:31], v[4:7], v[116:119], v[52:55]
	v_mfma_f32_16x16x32_f16 v[52:55], v[8:11], v[104:107], v[64:67]
	s_nop 2
	v_or_b32_e32 v64, s12, v84
	v_ashrrev_i32_e32 v65, 31, v64
	v_mfma_f32_16x16x32_f16 v[60:63], v[4:7], v[104:107], v[60:63]
	v_mfma_f32_16x16x32_f16 v[44:47], v[4:7], v[108:111], v[56:59]
	s_waitcnt lgkmcnt(0)
	v_mfma_f32_16x16x32_f16 v[12:15], v[4:7], v[120:123], v[48:51]
	v_mfma_f32_16x16x32_f16 v[24:27], v[8:11], v[116:119], v[36:39]
	v_mfma_f32_16x16x32_f16 v[56:59], v[96:99], v[104:107], v[68:71]
	v_mfma_f32_16x16x32_f16 v[36:39], v[96:99], v[108:111], v[20:23]
	v_mfma_f32_16x16x32_f16 v[20:23], v[96:99], v[116:119], v[16:19]
	v_mfma_f32_16x16x32_f16 v[4:7], v[96:99], v[120:123], v[72:75]
	v_lshlrev_b64 v[96:97], 2, v[64:65]
	v_lshl_add_u64 v[64:65], s[2:3], 0, v[96:97]
	v_mfma_f32_16x16x32_f16 v[40:43], v[8:11], v[108:111], v[40:43]
	v_mfma_f32_16x16x32_f16 v[8:11], v[8:11], v[120:123], v[32:35]
	v_mfma_f32_16x16x32_f16 v[32:35], v[100:103], v[108:111], v[92:95]
	s_nop 2
	v_add_u32_e32 v92, s0, v85
	s_movk_i32 s0, 0x5000
	v_mfma_f32_16x16x32_f16 v[48:51], v[100:103], v[104:107], v[80:83]
	v_ashrrev_i32_e32 v93, 31, v92
	v_or_b32_e32 v94, 48, v92
	v_ashrrev_i32_e32 v95, 31, v94
	v_add_co_u32_e32 v80, vcc, s0, v64
	v_mfma_f32_16x16x32_f16 v[16:19], v[100:103], v[116:119], v[0:3]
	s_nop 0
	v_addc_co_u32_e32 v81, vcc, 0, v65, vcc
	global_load_dword v64, v[80:81], off
	v_mfma_f32_16x16x32_f16 v[0:3], v[100:103], v[120:123], v[76:79]
	v_lshl_add_u32 v65, v92, 12, v96
	v_add_u32_e32 v66, 0x1000, v65
	v_add_u32_e32 v67, 0x3000, v65
	v_add_u32_e32 v68, 0x11000, v65
	v_add_u32_e32 v69, 0x13000, v65
	v_add_u32_e32 v70, 0x21000, v65
	v_add_u32_e32 v71, 0x23000, v65
	v_add_u32_e32 v72, 0x31000, v65
	v_add_u32_e32 v73, 0x33000, v65
	v_lshlrev_b32_e32 v176, 3, v92
	v_add_u32_e32 v176, 0x1e200000, v176
	v_mov_b32_e32 v178, s71
	v_mul_u32_u24_e32 v178, 3, v178
	v_add_u32_e32 v178, 0, v178
	v_lshl_add_u32 v177, v178, 12, v96
	global_load_dwordx2 v[136:137], v176, s[30:31] offset:0
	global_load_dwordx2 v[138:139], v176, s[30:31] offset:8
	global_load_dwordx2 v[140:141], v176, s[30:31] offset:16
	global_load_dwordx2 v[142:143], v176, s[30:31] offset:24
	global_load_dwordx2 v[144:145], v176, s[30:31] offset:128
	global_load_dwordx2 v[146:147], v176, s[30:31] offset:136
	global_load_dwordx2 v[148:149], v176, s[30:31] offset:144
	global_load_dwordx2 v[150:151], v176, s[30:31] offset:152
	global_load_dwordx2 v[152:153], v176, s[30:31] offset:256
	global_load_dwordx2 v[154:155], v176, s[30:31] offset:264
	global_load_dwordx2 v[156:157], v176, s[30:31] offset:272
	global_load_dwordx2 v[158:159], v176, s[30:31] offset:280
	global_load_dwordx2 v[160:161], v176, s[30:31] offset:384
	global_load_dwordx2 v[162:163], v176, s[30:31] offset:392
	global_load_dwordx2 v[164:165], v176, s[30:31] offset:400
	global_load_dwordx2 v[166:167], v176, s[30:31] offset:408
	global_load_dword v168, v177, s[24:25] offset:0
	global_load_dword v172, v177, s[26:27] offset:0
	global_load_dword v169, v177, s[24:25] offset:64
	global_load_dword v173, v177, s[26:27] offset:64
	global_load_dword v170, v177, s[24:25] offset:128
	global_load_dword v174, v177, s[26:27] offset:128
	global_load_dword v171, v177, s[24:25] offset:192
	global_load_dword v175, v177, s[26:27] offset:192
	global_load_dword v74, v[80:81], off offset:0
	global_load_dword v75, v[80:81], off offset:64
	global_load_dword v76, v[80:81], off offset:128
	global_load_dword v77, v[80:81], off offset:192
	global_load_dword v78, v66, s[28:29] offset:-4096
	global_load_dword v79, v66, s[28:29] offset:0
	global_load_dword v82, v67, s[28:29] offset:-4096
	global_load_dword v83, v67, s[28:29] offset:0
	global_load_dword v91, v68, s[28:29] offset:-4096
	global_load_dword v93, v68, s[28:29] offset:0
	global_load_dword v94, v69, s[28:29] offset:-4096
	global_load_dword v95, v69, s[28:29] offset:0
	global_load_dword v97, v70, s[28:29] offset:-4096
	global_load_dword v98, v70, s[28:29] offset:0
	global_load_dword v99, v71, s[28:29] offset:-4096
	global_load_dword v100, v71, s[28:29] offset:0
	global_load_dword v101, v72, s[28:29] offset:-4096
	global_load_dword v102, v72, s[28:29] offset:0
	global_load_dword v103, v73, s[28:29] offset:-4096
	global_load_dword v104, v73, s[28:29] offset:0
	global_load_dword v105, v66, s[28:29] offset:-4032
	global_load_dword v106, v66, s[28:29] offset:64
	global_load_dword v107, v67, s[28:29] offset:-4032
	global_load_dword v108, v67, s[28:29] offset:64
	global_load_dword v109, v68, s[28:29] offset:-4032
	global_load_dword v110, v68, s[28:29] offset:64
	global_load_dword v111, v69, s[28:29] offset:-4032
	global_load_dword v112, v69, s[28:29] offset:64
	global_load_dword v116, v70, s[28:29] offset:-4032
	global_load_dword v117, v70, s[28:29] offset:64
	global_load_dword v118, v71, s[28:29] offset:-4032
	global_load_dword v119, v71, s[28:29] offset:64
	global_load_dword v120, v72, s[28:29] offset:-4032
	global_load_dword v121, v72, s[28:29] offset:64
	global_load_dword v122, v73, s[28:29] offset:-4032
	global_load_dword v123, v73, s[28:29] offset:64
	s_waitcnt vmcnt(32)
	v_add_f32_e32 v74, 1.0, v74
	v_add_f32_e32 v75, 1.0, v75
	v_add_f32_e32 v76, 1.0, v76
	v_add_f32_e32 v77, 1.0, v77
	s_waitcnt vmcnt(31)
	v_sub_f32_e32 v78, v78, v136
	v_mul_f32_e32 v78, v78, v137
	v_fma_f32 v78, v168, v78, v172
	v_mul_f32_e32 v60, v60, v74
	v_fmac_f32_e32 v60, 0x3fb504f3, v78
	global_load_dword v78, v66, s[28:29] offset:-3968
	global_store_dword v66, v60, s[28:29] offset:-4096
	s_waitcnt vmcnt(32)
	v_sub_f32_e32 v79, v79, v138
	v_mul_f32_e32 v79, v79, v139
	v_fma_f32 v79, v168, v79, v172
	v_mul_f32_e32 v61, v61, v74
	v_fmac_f32_e32 v61, 0x3fb504f3, v79
	global_load_dword v79, v66, s[28:29] offset:128
	global_store_dword v66, v61, s[28:29] offset:0
	s_waitcnt vmcnt(33)
	v_sub_f32_e32 v82, v82, v140
	v_mul_f32_e32 v82, v82, v141
	v_fma_f32 v82, v168, v82, v172
	v_mul_f32_e32 v62, v62, v74
	v_fmac_f32_e32 v62, 0x3fb504f3, v82
	global_load_dword v82, v67, s[28:29] offset:-3968
	global_store_dword v67, v62, s[28:29] offset:-4096
	s_waitcnt vmcnt(34)
	v_sub_f32_e32 v83, v83, v142
	v_mul_f32_e32 v83, v83, v143
	v_fma_f32 v83, v168, v83, v172
	v_mul_f32_e32 v63, v63, v74
	v_fmac_f32_e32 v63, 0x3fb504f3, v83
	global_load_dword v83, v67, s[28:29] offset:128
	global_store_dword v67, v63, s[28:29] offset:0
	s_waitcnt vmcnt(35)
	v_sub_f32_e32 v91, v91, v144
	v_mul_f32_e32 v91, v91, v145
	v_fma_f32 v91, v168, v91, v172
	v_mul_f32_e32 v52, v52, v74
	v_fmac_f32_e32 v52, 0x3fb504f3, v91
	global_load_dword v91, v68, s[28:29] offset:-3968
	global_store_dword v68, v52, s[28:29] offset:-4096
	s_waitcnt vmcnt(36)
	v_sub_f32_e32 v93, v93, v146
	v_mul_f32_e32 v93, v93, v147
	v_fma_f32 v93, v168, v93, v172
	v_mul_f32_e32 v53, v53, v74
	v_fmac_f32_e32 v53, 0x3fb504f3, v93
	global_load_dword v93, v68, s[28:29] offset:128
	global_store_dword v68, v53, s[28:29] offset:0
	s_waitcnt vmcnt(37)
	v_sub_f32_e32 v94, v94, v148
	v_mul_f32_e32 v94, v94, v149
	v_fma_f32 v94, v168, v94, v172
	v_mul_f32_e32 v54, v54, v74
	v_fmac_f32_e32 v54, 0x3fb504f3, v94
	global_load_dword v94, v69, s[28:29] offset:-3968
	global_store_dword v69, v54, s[28:29] offset:-4096
	s_waitcnt vmcnt(38)
	v_sub_f32_e32 v95, v95, v150
	v_mul_f32_e32 v95, v95, v151
	v_fma_f32 v95, v168, v95, v172
	v_mul_f32_e32 v55, v55, v74
	v_fmac_f32_e32 v55, 0x3fb504f3, v95
	global_load_dword v95, v69, s[28:29] offset:128
	global_store_dword v69, v55, s[28:29] offset:0
	s_waitcnt vmcnt(39)
	v_sub_f32_e32 v97, v97, v152
	v_mul_f32_e32 v97, v97, v153
	v_fma_f32 v97, v168, v97, v172
	v_mul_f32_e32 v56, v56, v74
	v_fmac_f32_e32 v56, 0x3fb504f3, v97
	global_load_dword v97, v70, s[28:29] offset:-3968
	global_store_dword v70, v56, s[28:29] offset:-4096
	s_waitcnt vmcnt(40)
	v_sub_f32_e32 v98, v98, v154
	v_mul_f32_e32 v98, v98, v155
	v_fma_f32 v98, v168, v98, v172
	v_mul_f32_e32 v57, v57, v74
	v_fmac_f32_e32 v57, 0x3fb504f3, v98
	global_load_dword v98, v70, s[28:29] offset:128
	global_store_dword v70, v57, s[28:29] offset:0
	s_waitcnt vmcnt(41)
	v_sub_f32_e32 v99, v99, v156
	v_mul_f32_e32 v99, v99, v157
	v_fma_f32 v99, v168, v99, v172
	v_mul_f32_e32 v58, v58, v74
	v_fmac_f32_e32 v58, 0x3fb504f3, v99
	global_load_dword v99, v71, s[28:29] offset:-3968
	global_store_dword v71, v58, s[28:29] offset:-4096
	s_waitcnt vmcnt(42)
	v_sub_f32_e32 v100, v100, v158
	v_mul_f32_e32 v100, v100, v159
	v_fma_f32 v100, v168, v100, v172
	v_mul_f32_e32 v59, v59, v74
	v_fmac_f32_e32 v59, 0x3fb504f3, v100
	global_load_dword v100, v71, s[28:29] offset:128
	global_store_dword v71, v59, s[28:29] offset:0
	s_waitcnt vmcnt(43)
	v_sub_f32_e32 v101, v101, v160
	v_mul_f32_e32 v101, v101, v161
	v_fma_f32 v101, v168, v101, v172
	v_mul_f32_e32 v48, v48, v74
	v_fmac_f32_e32 v48, 0x3fb504f3, v101
	global_load_dword v101, v72, s[28:29] offset:-3968
	global_store_dword v72, v48, s[28:29] offset:-4096
	s_waitcnt vmcnt(44)
	v_sub_f32_e32 v102, v102, v162
	v_mul_f32_e32 v102, v102, v163
	v_fma_f32 v102, v168, v102, v172
	v_mul_f32_e32 v49, v49, v74
	v_fmac_f32_e32 v49, 0x3fb504f3, v102
	global_load_dword v102, v72, s[28:29] offset:128
	global_store_dword v72, v49, s[28:29] offset:0
	s_waitcnt vmcnt(45)
	v_sub_f32_e32 v103, v103, v164
	v_mul_f32_e32 v103, v103, v165
	v_fma_f32 v103, v168, v103, v172
	v_mul_f32_e32 v50, v50, v74
	v_fmac_f32_e32 v50, 0x3fb504f3, v103
	global_load_dword v103, v73, s[28:29] offset:-3968
	global_store_dword v73, v50, s[28:29] offset:-4096
	s_waitcnt vmcnt(46)
	v_sub_f32_e32 v104, v104, v166
	v_mul_f32_e32 v104, v104, v167
	v_fma_f32 v104, v168, v104, v172
	v_mul_f32_e32 v51, v51, v74
	v_fmac_f32_e32 v51, 0x3fb504f3, v104
	global_load_dword v104, v73, s[28:29] offset:128
	global_store_dword v73, v51, s[28:29] offset:0
	s_waitcnt vmcnt(47)
	v_sub_f32_e32 v105, v105, v136
	v_mul_f32_e32 v105, v105, v137
	v_fma_f32 v105, v169, v105, v173
	v_mul_f32_e32 v44, v44, v75
	v_fmac_f32_e32 v44, 0x3fb504f3, v105
	global_load_dword v105, v66, s[28:29] offset:-3904
	global_store_dword v66, v44, s[28:29] offset:-4032
	s_waitcnt vmcnt(48)
	v_sub_f32_e32 v106, v106, v138
	v_mul_f32_e32 v106, v106, v139
	v_fma_f32 v106, v169, v106, v173
	v_mul_f32_e32 v45, v45, v75
	v_fmac_f32_e32 v45, 0x3fb504f3, v106
	global_load_dword v106, v66, s[28:29] offset:192
	global_store_dword v66, v45, s[28:29] offset:64
	s_waitcnt vmcnt(49)
	v_sub_f32_e32 v107, v107, v140
	v_mul_f32_e32 v107, v107, v141
	v_fma_f32 v107, v169, v107, v173
	v_mul_f32_e32 v46, v46, v75
	v_fmac_f32_e32 v46, 0x3fb504f3, v107
	global_load_dword v107, v67, s[28:29] offset:-3904
	global_store_dword v67, v46, s[28:29] offset:-4032
	s_waitcnt vmcnt(50)
	v_sub_f32_e32 v108, v108, v142
	v_mul_f32_e32 v108, v108, v143
	v_fma_f32 v108, v169, v108, v173
	v_mul_f32_e32 v47, v47, v75
	v_fmac_f32_e32 v47, 0x3fb504f3, v108
	global_load_dword v108, v67, s[28:29] offset:192
	global_store_dword v67, v47, s[28:29] offset:64
	s_waitcnt vmcnt(51)
	v_sub_f32_e32 v109, v109, v144
	v_mul_f32_e32 v109, v109, v145
	v_fma_f32 v109, v169, v109, v173
	v_mul_f32_e32 v40, v40, v75
	v_fmac_f32_e32 v40, 0x3fb504f3, v109
	global_load_dword v109, v68, s[28:29] offset:-3904
	global_store_dword v68, v40, s[28:29] offset:-4032
	s_waitcnt vmcnt(52)
	v_sub_f32_e32 v110, v110, v146
	v_mul_f32_e32 v110, v110, v147
	v_fma_f32 v110, v169, v110, v173
	v_mul_f32_e32 v41, v41, v75
	v_fmac_f32_e32 v41, 0x3fb504f3, v110
	global_load_dword v110, v68, s[28:29] offset:192
	global_store_dword v68, v41, s[28:29] offset:64
	s_waitcnt vmcnt(53)
	v_sub_f32_e32 v111, v111, v148
	v_mul_f32_e32 v111, v111, v149
	v_fma_f32 v111, v169, v111, v173
	v_mul_f32_e32 v42, v42, v75
	v_fmac_f32_e32 v42, 0x3fb504f3, v111
	global_load_dword v111, v69, s[28:29] offset:-3904
	global_store_dword v69, v42, s[28:29] offset:-4032
	s_waitcnt vmcnt(54)
	v_sub_f32_e32 v112, v112, v150
	v_mul_f32_e32 v112, v112, v151
	v_fma_f32 v112, v169, v112, v173
	v_mul_f32_e32 v43, v43, v75
	v_fmac_f32_e32 v43, 0x3fb504f3, v112
	global_load_dword v112, v69, s[28:29] offset:192
	global_store_dword v69, v43, s[28:29] offset:64
	s_waitcnt vmcnt(55)
	v_sub_f32_e32 v116, v116, v152
	v_mul_f32_e32 v116, v116, v153
	v_fma_f32 v116, v169, v116, v173
	v_mul_f32_e32 v36, v36, v75
	v_fmac_f32_e32 v36, 0x3fb504f3, v116
	global_load_dword v116, v70, s[28:29] offset:-3904
	global_store_dword v70, v36, s[28:29] offset:-4032
	s_waitcnt vmcnt(56)
	v_sub_f32_e32 v117, v117, v154
	v_mul_f32_e32 v117, v117, v155
	v_fma_f32 v117, v169, v117, v173
	v_mul_f32_e32 v37, v37, v75
	v_fmac_f32_e32 v37, 0x3fb504f3, v117
	global_load_dword v117, v70, s[28:29] offset:192
	global_store_dword v70, v37, s[28:29] offset:64
	s_waitcnt vmcnt(57)
	v_sub_f32_e32 v118, v118, v156
	v_mul_f32_e32 v118, v118, v157
	v_fma_f32 v118, v169, v118, v173
	v_mul_f32_e32 v38, v38, v75
	v_fmac_f32_e32 v38, 0x3fb504f3, v118
	global_load_dword v118, v71, s[28:29] offset:-3904
	global_store_dword v71, v38, s[28:29] offset:-4032
	s_waitcnt vmcnt(58)
	v_sub_f32_e32 v119, v119, v158
	v_mul_f32_e32 v119, v119, v159
	v_fma_f32 v119, v169, v119, v173
	v_mul_f32_e32 v39, v39, v75
	v_fmac_f32_e32 v39, 0x3fb504f3, v119
	global_load_dword v119, v71, s[28:29] offset:192
	global_store_dword v71, v39, s[28:29] offset:64
	s_waitcnt vmcnt(59)
	v_sub_f32_e32 v120, v120, v160
	v_mul_f32_e32 v120, v120, v161
	v_fma_f32 v120, v169, v120, v173
	v_mul_f32_e32 v32, v32, v75
	v_fmac_f32_e32 v32, 0x3fb504f3, v120
	global_load_dword v120, v72, s[28:29] offset:-3904
	global_store_dword v72, v32, s[28:29] offset:-4032
	s_waitcnt vmcnt(60)
	v_sub_f32_e32 v121, v121, v162
	v_mul_f32_e32 v121, v121, v163
	v_fma_f32 v121, v169, v121, v173
	v_mul_f32_e32 v33, v33, v75
	v_fmac_f32_e32 v33, 0x3fb504f3, v121
	global_load_dword v121, v72, s[28:29] offset:192
	global_store_dword v72, v33, s[28:29] offset:64
	s_waitcnt vmcnt(61)
	v_sub_f32_e32 v122, v122, v164
	v_mul_f32_e32 v122, v122, v165
	v_fma_f32 v122, v169, v122, v173
	v_mul_f32_e32 v34, v34, v75
	v_fmac_f32_e32 v34, 0x3fb504f3, v122
	global_load_dword v122, v73, s[28:29] offset:-3904
	global_store_dword v73, v34, s[28:29] offset:-4032
	s_waitcnt vmcnt(62)
	v_sub_f32_e32 v123, v123, v166
	v_mul_f32_e32 v123, v123, v167
	v_fma_f32 v123, v169, v123, v173
	v_mul_f32_e32 v35, v35, v75
	v_fmac_f32_e32 v35, 0x3fb504f3, v123
	global_load_dword v123, v73, s[28:29] offset:192
	global_store_dword v73, v35, s[28:29] offset:64
	s_waitcnt vmcnt(63)
	v_sub_f32_e32 v78, v78, v136
	v_mul_f32_e32 v78, v78, v137
	v_fma_f32 v78, v170, v78, v174
	v_mul_f32_e32 v28, v28, v76
	v_fmac_f32_e32 v28, 0x3fb504f3, v78
	global_store_dword v66, v28, s[28:29] offset:-3968
	s_waitcnt vmcnt(62)
	v_sub_f32_e32 v79, v79, v138
	v_mul_f32_e32 v79, v79, v139
	v_fma_f32 v79, v170, v79, v174
	v_mul_f32_e32 v29, v29, v76
	v_fmac_f32_e32 v29, 0x3fb504f3, v79
	global_store_dword v66, v29, s[28:29] offset:128
	s_waitcnt vmcnt(61)
	v_sub_f32_e32 v82, v82, v140
	v_mul_f32_e32 v82, v82, v141
	v_fma_f32 v82, v170, v82, v174
	v_mul_f32_e32 v30, v30, v76
	v_fmac_f32_e32 v30, 0x3fb504f3, v82
	global_store_dword v67, v30, s[28:29] offset:-3968
	s_waitcnt vmcnt(60)
	v_sub_f32_e32 v83, v83, v142
	v_mul_f32_e32 v83, v83, v143
	v_fma_f32 v83, v170, v83, v174
	v_mul_f32_e32 v31, v31, v76
	v_fmac_f32_e32 v31, 0x3fb504f3, v83
	global_store_dword v67, v31, s[28:29] offset:128
	s_waitcnt vmcnt(59)
	v_sub_f32_e32 v91, v91, v144
	v_mul_f32_e32 v91, v91, v145
	v_fma_f32 v91, v170, v91, v174
	v_mul_f32_e32 v24, v24, v76
	v_fmac_f32_e32 v24, 0x3fb504f3, v91
	global_store_dword v68, v24, s[28:29] offset:-3968
	s_waitcnt vmcnt(58)
	v_sub_f32_e32 v93, v93, v146
	v_mul_f32_e32 v93, v93, v147
	v_fma_f32 v93, v170, v93, v174
	v_mul_f32_e32 v25, v25, v76
	v_fmac_f32_e32 v25, 0x3fb504f3, v93
	global_store_dword v68, v25, s[28:29] offset:128
	s_waitcnt vmcnt(57)
	v_sub_f32_e32 v94, v94, v148
	v_mul_f32_e32 v94, v94, v149
	v_fma_f32 v94, v170, v94, v174
	v_mul_f32_e32 v26, v26, v76
	v_fmac_f32_e32 v26, 0x3fb504f3, v94
	global_store_dword v69, v26, s[28:29] offset:-3968
	s_waitcnt vmcnt(56)
	v_sub_f32_e32 v95, v95, v150
	v_mul_f32_e32 v95, v95, v151
	v_fma_f32 v95, v170, v95, v174
	v_mul_f32_e32 v27, v27, v76
	v_fmac_f32_e32 v27, 0x3fb504f3, v95
	global_store_dword v69, v27, s[28:29] offset:128
	s_waitcnt vmcnt(55)
	v_sub_f32_e32 v97, v97, v152
	v_mul_f32_e32 v97, v97, v153
	v_fma_f32 v97, v170, v97, v174
	v_mul_f32_e32 v20, v20, v76
	v_fmac_f32_e32 v20, 0x3fb504f3, v97
	global_store_dword v70, v20, s[28:29] offset:-3968
	s_waitcnt vmcnt(54)
	v_sub_f32_e32 v98, v98, v154
	v_mul_f32_e32 v98, v98, v155
	v_fma_f32 v98, v170, v98, v174
	v_mul_f32_e32 v21, v21, v76
	v_fmac_f32_e32 v21, 0x3fb504f3, v98
	global_store_dword v70, v21, s[28:29] offset:128
	s_waitcnt vmcnt(53)
	v_sub_f32_e32 v99, v99, v156
	v_mul_f32_e32 v99, v99, v157
	v_fma_f32 v99, v170, v99, v174
	v_mul_f32_e32 v22, v22, v76
	v_fmac_f32_e32 v22, 0x3fb504f3, v99
	global_store_dword v71, v22, s[28:29] offset:-3968
	s_waitcnt vmcnt(52)
	v_sub_f32_e32 v100, v100, v158
	v_mul_f32_e32 v100, v100, v159
	v_fma_f32 v100, v170, v100, v174
	v_mul_f32_e32 v23, v23, v76
	v_fmac_f32_e32 v23, 0x3fb504f3, v100
	global_store_dword v71, v23, s[28:29] offset:128
	s_waitcnt vmcnt(51)
	v_sub_f32_e32 v101, v101, v160
	v_mul_f32_e32 v101, v101, v161
	v_fma_f32 v101, v170, v101, v174
	v_mul_f32_e32 v16, v16, v76
	v_fmac_f32_e32 v16, 0x3fb504f3, v101
	global_store_dword v72, v16, s[28:29] offset:-3968
	s_waitcnt vmcnt(50)
	v_sub_f32_e32 v102, v102, v162
	v_mul_f32_e32 v102, v102, v163
	v_fma_f32 v102, v170, v102, v174
	v_mul_f32_e32 v17, v17, v76
	v_fmac_f32_e32 v17, 0x3fb504f3, v102
	global_store_dword v72, v17, s[28:29] offset:128
	s_waitcnt vmcnt(49)
	v_sub_f32_e32 v103, v103, v164
	v_mul_f32_e32 v103, v103, v165
	v_fma_f32 v103, v170, v103, v174
	v_mul_f32_e32 v18, v18, v76
	v_fmac_f32_e32 v18, 0x3fb504f3, v103
	global_store_dword v73, v18, s[28:29] offset:-3968
	s_waitcnt vmcnt(48)
	v_sub_f32_e32 v104, v104, v166
	v_mul_f32_e32 v104, v104, v167
	v_fma_f32 v104, v170, v104, v174
	v_mul_f32_e32 v19, v19, v76
	v_fmac_f32_e32 v19, 0x3fb504f3, v104
	global_store_dword v73, v19, s[28:29] offset:128
	s_waitcnt vmcnt(47)
	v_sub_f32_e32 v105, v105, v136
	v_mul_f32_e32 v105, v105, v137
	v_fma_f32 v105, v171, v105, v175
	v_mul_f32_e32 v12, v12, v77
	v_fmac_f32_e32 v12, 0x3fb504f3, v105
	global_store_dword v66, v12, s[28:29] offset:-3904
	s_waitcnt vmcnt(46)
	v_sub_f32_e32 v106, v106, v138
	v_mul_f32_e32 v106, v106, v139
	v_fma_f32 v106, v171, v106, v175
	v_mul_f32_e32 v13, v13, v77
	v_fmac_f32_e32 v13, 0x3fb504f3, v106
	global_store_dword v66, v13, s[28:29] offset:192
	s_waitcnt vmcnt(45)
	v_sub_f32_e32 v107, v107, v140
	v_mul_f32_e32 v107, v107, v141
	v_fma_f32 v107, v171, v107, v175
	v_mul_f32_e32 v14, v14, v77
	v_fmac_f32_e32 v14, 0x3fb504f3, v107
	global_store_dword v67, v14, s[28:29] offset:-3904
	s_waitcnt vmcnt(44)
	v_sub_f32_e32 v108, v108, v142
	v_mul_f32_e32 v108, v108, v143
	v_fma_f32 v108, v171, v108, v175
	v_mul_f32_e32 v15, v15, v77
	v_fmac_f32_e32 v15, 0x3fb504f3, v108
	global_store_dword v67, v15, s[28:29] offset:192
	s_waitcnt vmcnt(43)
	v_sub_f32_e32 v109, v109, v144
	v_mul_f32_e32 v109, v109, v145
	v_fma_f32 v109, v171, v109, v175
	v_mul_f32_e32 v8, v8, v77
	v_fmac_f32_e32 v8, 0x3fb504f3, v109
	global_store_dword v68, v8, s[28:29] offset:-3904
	s_waitcnt vmcnt(42)
	v_sub_f32_e32 v110, v110, v146
	v_mul_f32_e32 v110, v110, v147
	v_fma_f32 v110, v171, v110, v175
	v_mul_f32_e32 v9, v9, v77
	v_fmac_f32_e32 v9, 0x3fb504f3, v110
	global_store_dword v68, v9, s[28:29] offset:192
	s_waitcnt vmcnt(41)
	v_sub_f32_e32 v111, v111, v148
	v_mul_f32_e32 v111, v111, v149
	v_fma_f32 v111, v171, v111, v175
	v_mul_f32_e32 v10, v10, v77
	v_fmac_f32_e32 v10, 0x3fb504f3, v111
	global_store_dword v69, v10, s[28:29] offset:-3904
	s_waitcnt vmcnt(40)
	v_sub_f32_e32 v112, v112, v150
	v_mul_f32_e32 v112, v112, v151
	v_fma_f32 v112, v171, v112, v175
	v_mul_f32_e32 v11, v11, v77
	v_fmac_f32_e32 v11, 0x3fb504f3, v112
	global_store_dword v69, v11, s[28:29] offset:192
	s_waitcnt vmcnt(39)
	v_sub_f32_e32 v116, v116, v152
	v_mul_f32_e32 v116, v116, v153
	v_fma_f32 v116, v171, v116, v175
	v_mul_f32_e32 v4, v4, v77
	v_fmac_f32_e32 v4, 0x3fb504f3, v116
	global_store_dword v70, v4, s[28:29] offset:-3904
	s_waitcnt vmcnt(38)
	v_sub_f32_e32 v117, v117, v154
	v_mul_f32_e32 v117, v117, v155
	v_fma_f32 v117, v171, v117, v175
	v_mul_f32_e32 v5, v5, v77
	v_fmac_f32_e32 v5, 0x3fb504f3, v117
	global_store_dword v70, v5, s[28:29] offset:192
	s_waitcnt vmcnt(37)
	v_sub_f32_e32 v118, v118, v156
	v_mul_f32_e32 v118, v118, v157
	v_fma_f32 v118, v171, v118, v175
	v_mul_f32_e32 v6, v6, v77
	v_fmac_f32_e32 v6, 0x3fb504f3, v118
	global_store_dword v71, v6, s[28:29] offset:-3904
	s_waitcnt vmcnt(36)
	v_sub_f32_e32 v119, v119, v158
	v_mul_f32_e32 v119, v119, v159
	v_fma_f32 v119, v171, v119, v175
	v_mul_f32_e32 v7, v7, v77
	v_fmac_f32_e32 v7, 0x3fb504f3, v119
	global_store_dword v71, v7, s[28:29] offset:192
	s_waitcnt vmcnt(35)
	v_sub_f32_e32 v120, v120, v160
	v_mul_f32_e32 v120, v120, v161
	v_fma_f32 v120, v171, v120, v175
	v_mul_f32_e32 v0, v0, v77
	v_fmac_f32_e32 v0, 0x3fb504f3, v120
	global_store_dword v72, v0, s[28:29] offset:-3904
	s_waitcnt vmcnt(34)
	v_sub_f32_e32 v121, v121, v162
	v_mul_f32_e32 v121, v121, v163
	v_fma_f32 v121, v171, v121, v175
	v_mul_f32_e32 v1, v1, v77
	v_fmac_f32_e32 v1, 0x3fb504f3, v121
	global_store_dword v72, v1, s[28:29] offset:192
	s_waitcnt vmcnt(33)
	v_sub_f32_e32 v122, v122, v164
	v_mul_f32_e32 v122, v122, v165
	v_fma_f32 v122, v171, v122, v175
	v_mul_f32_e32 v2, v2, v77
	v_fmac_f32_e32 v2, 0x3fb504f3, v122
	global_store_dword v73, v2, s[28:29] offset:-3904
	s_waitcnt vmcnt(32)
	v_sub_f32_e32 v123, v123, v166
	v_mul_f32_e32 v123, v123, v167
	v_fma_f32 v123, v171, v123, v175
	v_mul_f32_e32 v3, v3, v77
	v_fmac_f32_e32 v3, 0x3fb504f3, v123
	global_store_dword v73, v3, s[28:29] offset:192
	s_cbranch_scc0 .LBB0_600

.LBB0_615:
	s_or_b64 exec, exec, s[10:11]
	global_load_dwordx4 v[80:83], v[54:55], off offset:-2048
	global_load_dwordx4 v[84:87], v[54:55], off offset:-1024
	global_load_dwordx4 v[88:91], v[54:55], off
	global_load_dwordx4 v[92:95], v[54:55], off offset:1024
	v_add_u32_e32 v48, 1, v48
	s_mov_b64 s[4:5], 0x800
	s_waitcnt vmcnt(3)
	v_add_f32_e32 v49, 0, v80
	v_add_f32_e32 v49, v49, v81
	v_add_f32_e32 v49, v49, v82
	v_add_f32_e32 v49, v49, v83
	s_waitcnt vmcnt(2)
	v_add_f32_e32 v49, v49, v84
	v_add_f32_e32 v49, v49, v85
	v_add_f32_e32 v49, v49, v86
	v_add_f32_e32 v49, v49, v87
	s_waitcnt vmcnt(1)
	v_add_f32_e32 v49, v49, v88
	v_add_f32_e32 v49, v49, v89
	v_add_f32_e32 v49, v49, v90
	v_add_f32_e32 v49, v49, v91
	s_waitcnt vmcnt(0)
	v_add_f32_e32 v49, v49, v92
	v_add_f32_e32 v49, v49, v93
	v_add_f32_e32 v49, v49, v94
	v_add_f32_e32 v49, v49, v95
	ds_bpermute_b32 v96, v73, v49
	s_waitcnt lgkmcnt(0)
	v_add_f32_e32 v49, v49, v96
	ds_bpermute_b32 v96, v74, v49
	s_waitcnt lgkmcnt(0)
	v_add_f32_e32 v49, v49, v96
	ds_bpermute_b32 v96, v75, v49
	s_waitcnt lgkmcnt(0)
	v_add_f32_e32 v49, v49, v96
	ds_bpermute_b32 v96, v76, v49
	s_waitcnt lgkmcnt(0)
	v_add_f32_e32 v49, v49, v96
	ds_bpermute_b32 v96, v77, v49
	s_waitcnt lgkmcnt(0)
	v_add_f32_e32 v49, v49, v96
	ds_bpermute_b32 v96, v78, v49
	s_waitcnt lgkmcnt(0)
	v_add_f32_e32 v49, v49, v96
	v_mul_f32_e32 v96, 0x3a800000, v49
	v_mov_b32_e32 v252, v96
	v_pk_add_f32 v[80:81], v[80:81], v[96:97] op_sel_hi:[1,0] neg_lo:[0,1] neg_hi:[0,1]
	v_pk_add_f32 v[82:83], v[82:83], v[96:97] op_sel_hi:[1,0] neg_lo:[0,1] neg_hi:[0,1]
	v_pk_mul_f32 v[98:99], v[80:81], v[80:81]
	v_pk_mul_f32 v[100:101], v[82:83], v[82:83]
	v_add_f32_e32 v49, v98, v99
	v_pk_add_f32 v[84:85], v[84:85], v[96:97] op_sel_hi:[1,0] neg_lo:[0,1] neg_hi:[0,1]
	v_add_f32_e32 v49, v100, v49
	v_pk_mul_f32 v[102:103], v[84:85], v[84:85]
	v_add_f32_e32 v49, v101, v49
	v_pk_add_f32 v[86:87], v[86:87], v[96:97] op_sel_hi:[1,0] neg_lo:[0,1] neg_hi:[0,1]
	v_add_f32_e32 v49, v102, v49
	v_pk_mul_f32 v[104:105], v[86:87], v[86:87]
	v_add_f32_e32 v49, v103, v49
	v_pk_add_f32 v[88:89], v[88:89], v[96:97] op_sel_hi:[1,0] neg_lo:[0,1] neg_hi:[0,1]
	v_add_f32_e32 v49, v104, v49
	v_pk_mul_f32 v[106:107], v[88:89], v[88:89]
	v_add_f32_e32 v49, v105, v49
	v_pk_add_f32 v[90:91], v[90:91], v[96:97] op_sel_hi:[1,0] neg_lo:[0,1] neg_hi:[0,1]
	v_add_f32_e32 v49, v106, v49
	v_pk_mul_f32 v[108:109], v[90:91], v[90:91]
	v_add_f32_e32 v49, v107, v49
	v_pk_add_f32 v[92:93], v[92:93], v[96:97] op_sel_hi:[1,0] neg_lo:[0,1] neg_hi:[0,1]
	v_add_f32_e32 v49, v108, v49
	v_pk_mul_f32 v[110:111], v[92:93], v[92:93]
	v_add_f32_e32 v49, v109, v49
	v_pk_add_f32 v[94:95], v[94:95], v[96:97] op_sel_hi:[1,0] neg_lo:[0,1] neg_hi:[0,1]
	v_add_f32_e32 v49, v110, v49
	v_pk_mul_f32 v[96:97], v[94:95], v[94:95]
	v_add_f32_e32 v49, v111, v49
	v_add_f32_e32 v49, v96, v49
	v_add_f32_e32 v49, v97, v49
	ds_bpermute_b32 v96, v73, v49
	s_waitcnt lgkmcnt(0)
	v_add_f32_e32 v49, v49, v96
	ds_bpermute_b32 v96, v74, v49
	s_waitcnt lgkmcnt(0)
	v_add_f32_e32 v49, v49, v96
	ds_bpermute_b32 v96, v75, v49
	s_waitcnt lgkmcnt(0)
	v_add_f32_e32 v49, v49, v96
	ds_bpermute_b32 v96, v76, v49
	s_waitcnt lgkmcnt(0)
	v_add_f32_e32 v49, v49, v96
	ds_bpermute_b32 v96, v77, v49
	s_waitcnt lgkmcnt(0)
	v_add_f32_e32 v49, v49, v96
	ds_bpermute_b32 v96, v78, v49
	s_waitcnt lgkmcnt(0)
	v_add_f32_e32 v49, v49, v96
	v_fmamk_f32 v49, v49, 0x3a800000, v184
	v_cmp_gt_f32_e32 vcc, s49, v49
	v_mul_f32_e32 v96, 0x4b800000, v49
	s_nop 0
	v_cndmask_b32_e32 v49, v49, v96, vcc
	v_rsq_f32_e32 v49, v49
	s_nop 0
	v_mul_f32_e32 v96, 0x45800000, v49
	v_cndmask_b32_e32 v96, v49, v96, vcc
	v_mov_b32_e32 v253, v96
	v_lshlrev_b32_e32 v254, 3, v48
	v_add_u32_e32 v254, 0x1e1ffff8, v254
	s_mov_b64 exec, 1
	global_store_dwordx2 v254, v[252:253], s[30:31]
	s_mov_b64 exec, -1
	v_pk_mul_f32 v[80:81], v[80:81], v[96:97] op_sel_hi:[1,0]
	v_pk_mul_f32 v[82:83], v[82:83], v[96:97] op_sel_hi:[1,0]
	v_pk_fma_f32 v[80:81], v[0:1], v[80:81], v[8:9]
	v_pk_fma_f32 v[82:83], v[2:3], v[82:83], v[10:11]
	v_pk_mul_f32 v[84:85], v[84:85], v[96:97] op_sel_hi:[1,0]
	v_pk_mul_f32 v[86:87], v[86:87], v[96:97] op_sel_hi:[1,0]
	v_pk_mul_f32 v[88:89], v[88:89], v[96:97] op_sel_hi:[1,0]
	v_pk_mul_f32 v[90:91], v[90:91], v[96:97] op_sel_hi:[1,0]
	v_pk_mul_f32 v[92:93], v[92:93], v[96:97] op_sel_hi:[1,0]
	v_pk_mul_f32 v[94:95], v[94:95], v[96:97] op_sel_hi:[1,0]
	v_pk_fma_f32 v[84:85], v[4:5], v[84:85], v[12:13]
	v_pk_fma_f32 v[86:87], v[6:7], v[86:87], v[14:15]
	v_pk_fma_f32 v[88:89], v[16:17], v[88:89], v[24:25]
	v_pk_fma_f32 v[90:91], v[18:19], v[90:91], v[26:27]
	v_pk_fma_f32 v[92:93], v[20:21], v[92:93], v[28:29]
	v_pk_fma_f32 v[94:95], v[22:23], v[94:95], v[30:31]
	v_pk_fma_f32 v[80:81], v[66:67], v[80:81], v[44:45]
	v_cmp_ge_i32_e32 vcc, v48, v72
	v_med3_f32 v49, v80, s57, v194
	v_med3_f32 v96, v81, s57, v194
	v_pk_fma_f32 v[80:81], v[64:65], v[82:83], v[46:47]
	s_or_b64 s[8:9], vcc, s[8:9]
	v_med3_f32 v80, v80, s57, v194
	v_med3_f32 v81, v81, s57, v194
	v_cvt_pk_f16_f32 v49, v49, v80
	v_cvt_pk_f16_f32 v80, v96, v81
	v_and_b32_e32 v81, 0xffff0000, v80
	v_lshlrev_b32_e32 v80, 16, v80
	v_or_b32_sdwa v81, v81, v49 dst_sel:DWORD dst_unused:UNUSED_PAD src0_sel:DWORD src1_sel:WORD_1
	v_or_b32_sdwa v80, v80, v49 dst_sel:DWORD dst_unused:UNUSED_PAD src0_sel:DWORD src1_sel:WORD_0
	global_store_dwordx2 v[52:53], v[80:81], off
	v_pk_fma_f32 v[80:81], v[62:63], v[84:85], v[40:41]
	s_nop 0
	v_med3_f32 v49, v80, s57, v194
	v_med3_f32 v82, v81, s57, v194
	v_pk_fma_f32 v[80:81], v[60:61], v[86:87], v[42:43]
	s_nop 0
	v_med3_f32 v80, v80, s57, v194
	v_med3_f32 v81, v81, s57, v194
	v_cvt_pk_f16_f32 v49, v49, v80
	v_cvt_pk_f16_f32 v80, v82, v81
	v_and_b32_e32 v81, 0xffff0000, v80
	v_lshlrev_b32_e32 v80, 16, v80
	v_or_b32_sdwa v81, v81, v49 dst_sel:DWORD dst_unused:UNUSED_PAD src0_sel:DWORD src1_sel:WORD_1
	v_or_b32_sdwa v80, v80, v49 dst_sel:DWORD dst_unused:UNUSED_PAD src0_sel:DWORD src1_sel:WORD_0
	global_store_dwordx2 v[52:53], v[80:81], off offset:512
	v_pk_fma_f32 v[80:81], v[58:59], v[88:89], v[36:37]
	s_nop 0
	v_med3_f32 v49, v80, s57, v194
	v_med3_f32 v82, v81, s57, v194
	v_pk_fma_f32 v[80:81], v[56:57], v[90:91], v[38:39]
	s_nop 0
	v_med3_f32 v80, v80, s57, v194
	v_med3_f32 v81, v81, s57, v194
	v_cvt_pk_f16_f32 v49, v49, v80
	v_cvt_pk_f16_f32 v80, v82, v81
	v_and_b32_e32 v81, 0xffff0000, v80
	v_lshlrev_b32_e32 v80, 16, v80
	v_or_b32_sdwa v81, v81, v49 dst_sel:DWORD dst_unused:UNUSED_PAD src0_sel:DWORD src1_sel:WORD_1
	v_or_b32_sdwa v80, v80, v49 dst_sel:DWORD dst_unused:UNUSED_PAD src0_sel:DWORD src1_sel:WORD_0
	global_store_dwordx2 v[52:53], v[80:81], off offset:1024
	v_pk_fma_f32 v[80:81], v[70:71], v[92:93], v[32:33]
	s_nop 0
	v_med3_f32 v49, v80, s57, v194
	v_med3_f32 v82, v81, s57, v194
	v_pk_fma_f32 v[80:81], v[68:69], v[94:95], v[34:35]
	s_nop 0
	v_med3_f32 v80, v80, s57, v194
	v_med3_f32 v81, v81, s57, v194
	v_cvt_pk_f16_f32 v49, v49, v80
	v_cvt_pk_f16_f32 v80, v82, v81
	v_and_b32_e32 v81, 0xffff0000, v80
	v_lshlrev_b32_e32 v80, 16, v80
	v_or_b32_sdwa v81, v81, v49 dst_sel:DWORD dst_unused:UNUSED_PAD src0_sel:DWORD src1_sel:WORD_1
	v_or_b32_sdwa v80, v80, v49 dst_sel:DWORD dst_unused:UNUSED_PAD src0_sel:DWORD src1_sel:WORD_0
	global_store_dwordx2 v[52:53], v[80:81], off offset:1536
	v_lshl_add_u64 v[52:53], v[52:53], 0, s[4:5]
	s_mov_b64 s[4:5], 0x1000
	v_lshl_add_u64 v[54:55], v[54:55], 0, s[4:5]
	s_andn2_b64 exec, exec, s[8:9]
	s_cbranch_execz .LBB0_618

.LBB0_650:
	s_add_i32 s4, s13, 0xffff8000
	v_mov_b32_e32 v64, v182
	s_waitcnt vmcnt(0)
	s_waitcnt vmcnt(0) lgkmcnt(0)
	s_barrier
	s_and_b32 s14, s13, 0x8000
	s_and_b32 s15, s4, 0x8000
	v_or_b32_e32 v71, s15, v86
	v_lshrrev_b32_e32 v65, 4, v64
	v_ashrrev_i32_e32 v66, 3, v64
	v_add_u32_e32 v68, 0x100, v64
	v_lshl_add_u32 v67, v64, 4, s14
	v_add_u32_e32 v69, 0x200, v64
	v_add_u32_e32 v72, s0, v66
	v_bitop3_b32 v73, v65, 7, v64 bitop3:0x48
	v_ashrrev_i32_e32 v74, 3, v68
	s_add_u32 s8, s30, s2
	v_add_u32_e32 v70, 0x300, v64
	v_lshl_add_u32 v68, v68, 4, s14
	v_ashrrev_i32_e32 v75, 3, v69
	v_lshl_add_u32 v69, v69, 4, s14
	v_add_u32_e32 v77, 0x4000, v67
	v_add3_u32 v91, v71, v87, v88
	v_add3_u32 v80, v71, v89, v88
	v_mad_i64_i32 v[64:65], s[4:5], v72, s64, 0
	v_lshlrev_b32_e32 v81, 4, v73
	v_add_u32_e32 v71, s0, v74
	s_addc_u32 s9, s31, s3
	v_ashrrev_i32_e32 v76, 3, v70
	v_lshl_add_u32 v70, v70, 4, s14
	v_readfirstlane_b32 s17, v68
	v_add_u32_e32 v72, s0, v75
	v_readfirstlane_b32 s18, v69
	v_readfirstlane_b32 s20, v77
	v_add_u32_e32 v77, 0x4000, v68
	v_add_u32_e32 v79, 0x4000, v69
	v_or_b32_e32 v64, v64, v81
	v_mad_i64_i32 v[68:69], s[4:5], v71, s64, 0
	v_readfirstlane_b32 s16, v67
	v_add_u32_e32 v73, s0, v76
	v_readfirstlane_b32 s19, v70
	v_add_u32_e32 v83, 0x4000, v70
	v_mad_i64_i32 v[70:71], s[4:5], v72, s64, 0
	v_lshl_add_u64 v[64:65], s[8:9], 0, v[64:65]
	v_or_b32_e32 v68, v68, v81
	v_add_u32_e32 v66, s12, v66
	v_mad_i64_i32 v[72:73], s[4:5], v73, s64, 0
	v_or_b32_e32 v70, v70, v81
	v_lshl_add_u64 v[64:65], v[64:65], 0, s[88:89]
	v_lshl_add_u64 v[68:69], s[8:9], 0, v[68:69]
	s_mov_b32 m0, s16
	v_mad_i64_i32 v[66:67], s[4:5], v66, s64, 0
	v_add_u32_e32 v74, s12, v74
	v_or_b32_e32 v72, v72, v81
	v_lshl_add_u64 v[70:71], s[8:9], 0, v[70:71]
	global_load_lds_dwordx4 v[64:65], off
	v_lshl_add_u64 v[64:65], v[68:69], 0, s[88:89]
	s_mov_b32 m0, s17
	v_add_u32_e32 v78, s12, v75
	v_or_b32_e32 v66, v66, v81
	v_mad_i64_i32 v[74:75], s[4:5], v74, s64, 0
	v_lshl_add_u64 v[72:73], s[8:9], 0, v[72:73]
	v_lshl_add_u64 v[68:69], v[70:71], 0, s[88:89]
	global_load_lds_dwordx4 v[64:65], off
	s_mov_b32 m0, s18
	v_add_u32_e32 v82, s12, v76
	v_readfirstlane_b32 s21, v77
	v_mad_i64_i32 v[76:77], s[4:5], v78, s64, 0
	v_lshl_add_u64 v[66:67], s[8:9], 0, v[66:67]
	v_or_b32_e32 v74, v74, v81
	v_lshl_add_u64 v[70:71], v[72:73], 0, s[88:89]
	global_load_lds_dwordx4 v[68:69], off
	s_mov_b32 m0, s19
	v_readfirstlane_b32 s22, v79
	v_mad_i64_i32 v[78:79], s[4:5], v82, s64, 0
	v_or_b32_e32 v76, v76, v81
	v_lshl_add_u64 v[66:67], v[66:67], 0, s[6:7]
	v_lshl_add_u64 v[74:75], s[8:9], 0, v[74:75]
	global_load_lds_dwordx4 v[70:71], off
	s_mov_b32 m0, s20
	v_or_b32_e32 v78, v78, v81
	v_lshl_add_u64 v[76:77], s[8:9], 0, v[76:77]
	v_lshl_add_u64 v[72:73], v[74:75], 0, s[6:7]
	global_load_lds_dwordx4 v[66:67], off
	s_mov_b32 m0, s21
	v_readfirstlane_b32 s4, v83
	v_lshl_add_u64 v[78:79], s[8:9], 0, v[78:79]
	v_lshl_add_u64 v[74:75], v[76:77], 0, s[6:7]
	global_load_lds_dwordx4 v[72:73], off
	s_mov_b32 m0, s22
	v_lshl_add_u64 v[76:77], v[78:79], 0, s[6:7]
	global_load_lds_dwordx4 v[74:75], off
	s_mov_b32 m0, s4
	s_add_u32 s2, s2, 0x80
	global_load_lds_dwordx4 v[76:77], off
	ds_read_b128 v[64:67], v91
	ds_read_b128 v[68:71], v80 offset:16384
	ds_read_b128 v[72:75], v80 offset:18432
	ds_read_b128 v[76:79], v80 offset:20480
	ds_read_b128 v[80:83], v80 offset:22528
	s_waitcnt lgkmcnt(0)
	v_mfma_f32_16x16x32_f16 v[60:63], v[64:67], v[68:71], v[60:63]
	s_addc_u32 s3, s3, 0
	s_add_i32 s13, s13, 0x8000
	s_cmpk_eq_i32 s2, 0x1580
	v_mfma_f32_16x16x32_f16 v[56:59], v[64:67], v[72:75], v[56:59]
	v_mfma_f32_16x16x32_f16 v[52:55], v[64:67], v[76:79], v[52:55]
	v_mfma_f32_16x16x32_f16 v[48:51], v[64:67], v[80:83], v[48:51]
	ds_read_b128 v[64:67], v91 offset:2048
	s_waitcnt lgkmcnt(0)
	v_mfma_f32_16x16x32_f16 v[44:47], v[64:67], v[68:71], v[44:47]
	v_mfma_f32_16x16x32_f16 v[40:43], v[64:67], v[72:75], v[40:43]
	v_mfma_f32_16x16x32_f16 v[36:39], v[64:67], v[76:79], v[36:39]
	v_mfma_f32_16x16x32_f16 v[32:35], v[64:67], v[80:83], v[32:35]
	ds_read_b128 v[64:67], v91 offset:4096
	s_waitcnt lgkmcnt(0)
	v_mfma_f32_16x16x32_f16 v[24:27], v[64:67], v[68:71], v[24:27]
	v_mfma_f32_16x16x32_f16 v[20:23], v[64:67], v[72:75], v[20:23]
	v_mfma_f32_16x16x32_f16 v[16:19], v[64:67], v[76:79], v[16:19]
	v_mfma_f32_16x16x32_f16 v[12:15], v[64:67], v[80:83], v[12:15]
	ds_read_b128 v[64:67], v91 offset:6144
	s_waitcnt lgkmcnt(0)
	v_mfma_f32_16x16x32_f16 v[8:11], v[64:67], v[68:71], v[8:11]
	v_or_b32_e32 v68, s15, v90
	v_add3_u32 v91, v68, v87, v88
	v_add3_u32 v92, v68, v89, v88
	ds_read_b128 v[68:71], v91
	v_mfma_f32_16x16x32_f16 v[4:7], v[64:67], v[72:75], v[4:7]
	ds_read_b128 v[72:75], v92 offset:18432
	v_mfma_f32_16x16x32_f16 v[0:3], v[64:67], v[76:79], v[0:3]
	ds_read_b128 v[76:79], v92 offset:20480
	v_mfma_f32_16x16x32_f16 v[28:31], v[64:67], v[80:83], v[28:31]
	ds_read_b128 v[64:67], v92 offset:16384
	ds_read_b128 v[80:83], v92 offset:22528
	s_waitcnt lgkmcnt(1)
	v_mfma_f32_16x16x32_f16 v[60:63], v[68:71], v[64:67], v[60:63]
	v_mfma_f32_16x16x32_f16 v[56:59], v[68:71], v[72:75], v[56:59]
	v_mfma_f32_16x16x32_f16 v[52:55], v[68:71], v[76:79], v[52:55]
	s_waitcnt lgkmcnt(0)
	v_mfma_f32_16x16x32_f16 v[48:51], v[68:71], v[80:83], v[48:51]
	ds_read_b128 v[68:71], v91 offset:2048
	s_waitcnt lgkmcnt(0)
	v_mfma_f32_16x16x32_f16 v[44:47], v[68:71], v[64:67], v[44:47]
	v_mfma_f32_16x16x32_f16 v[40:43], v[68:71], v[72:75], v[40:43]
	v_mfma_f32_16x16x32_f16 v[36:39], v[68:71], v[76:79], v[36:39]
	v_mfma_f32_16x16x32_f16 v[32:35], v[68:71], v[80:83], v[32:35]
	ds_read_b128 v[68:71], v91 offset:4096
	s_waitcnt lgkmcnt(0)
	v_mfma_f32_16x16x32_f16 v[24:27], v[68:71], v[64:67], v[24:27]
	v_mfma_f32_16x16x32_f16 v[20:23], v[68:71], v[72:75], v[20:23]
	v_mfma_f32_16x16x32_f16 v[16:19], v[68:71], v[76:79], v[16:19]
	v_mfma_f32_16x16x32_f16 v[12:15], v[68:71], v[80:83], v[12:15]
	ds_read_b128 v[68:71], v91 offset:6144
	s_waitcnt lgkmcnt(0)
	v_mfma_f32_16x16x32_f16 v[8:11], v[68:71], v[64:67], v[8:11]
	v_mfma_f32_16x16x32_f16 v[4:7], v[68:71], v[72:75], v[4:7]
	v_mfma_f32_16x16x32_f16 v[0:3], v[68:71], v[76:79], v[0:3]
	v_mfma_f32_16x16x32_f16 v[28:31], v[68:71], v[80:83], v[28:31]
	s_cbranch_scc0 .LBB0_650
	v_add_u32_e32 v80, s14, v86
	v_add3_u32 v76, v80, v87, v88
	v_add3_u32 v91, v80, v89, v88
	s_waitcnt vmcnt(0)
	s_barrier
	ds_read_b128 v[64:67], v76
	ds_read_b128 v[68:71], v76 offset:2048
	ds_read_b128 v[72:75], v76 offset:4096
	ds_read_b128 v[76:79], v76 offset:6144
	ds_read_b128 v[80:83], v91 offset:16384
	ds_read_b128 v[92:95], v91 offset:18432
	ds_read_b128 v[96:99], v91 offset:20480
	ds_read_b128 v[100:103], v91 offset:22528
	s_waitcnt lgkmcnt(3)
	v_mfma_f32_16x16x32_f16 v[60:63], v[64:67], v[80:83], v[60:63]
	s_ashr_i32 s2, s0, 31
	s_lshr_b32 s2, s2, 19
	s_add_i32 s2, s0, s2
	s_waitcnt lgkmcnt(2)
	v_mfma_f32_16x16x32_f16 v[56:59], v[64:67], v[92:95], v[56:59]
	s_ashr_i32 s2, s2, 13
	s_add_i32 s2, s2, s10
	s_mul_hi_i32 s3, s2, 0x9000
	s_waitcnt lgkmcnt(1)
	v_mfma_f32_16x16x32_f16 v[52:55], v[64:67], v[96:99], v[52:55]
	s_mul_i32 s2, s2, 0x9000
	s_add_u32 s2, s50, s2
	s_addc_u32 s3, s51, s3
	s_waitcnt lgkmcnt(0)
	v_mfma_f32_16x16x32_f16 v[48:51], v[64:67], v[100:103], v[48:51]
	s_add_i32 s11, s11, s59
	s_cmpk_gt_i32 s11, 0x7ff
	v_mfma_f32_16x16x32_f16 v[64:67], v[68:71], v[80:83], v[44:47]
	v_mfma_f32_16x16x32_f16 v[40:43], v[68:71], v[92:95], v[40:43]
	v_mfma_f32_16x16x32_f16 v[36:39], v[68:71], v[96:99], v[36:39]
	v_mfma_f32_16x16x32_f16 v[32:35], v[68:71], v[100:103], v[32:35]
	v_mfma_f32_16x16x32_f16 v[68:71], v[72:75], v[80:83], v[24:27]
	v_mfma_f32_16x16x32_f16 v[20:23], v[72:75], v[92:95], v[20:23]
	v_mfma_f32_16x16x32_f16 v[16:19], v[72:75], v[96:99], v[16:19]
	v_mfma_f32_16x16x32_f16 v[72:75], v[72:75], v[100:103], v[12:15]
	s_nop 2
	v_add_u32_e32 v12, s14, v90
	v_add3_u32 v13, v12, v87, v88
	v_add3_u32 v12, v12, v89, v88
	v_mfma_f32_16x16x32_f16 v[80:83], v[76:79], v[80:83], v[8:11]
	v_mfma_f32_16x16x32_f16 v[92:95], v[76:79], v[92:95], v[4:7]
	v_mfma_f32_16x16x32_f16 v[0:3], v[76:79], v[96:99], v[0:3]
	v_mfma_f32_16x16x32_f16 v[76:79], v[76:79], v[100:103], v[28:31]
	s_nop 0
	ds_read_b128 v[4:7], v13
	ds_read_b128 v[8:11], v13 offset:2048
	ds_read_b128 v[96:99], v13 offset:4096
	ds_read_b128 v[100:103], v13 offset:6144
	ds_read_b128 v[104:107], v12 offset:16384
	ds_read_b128 v[108:111], v12 offset:18432
	ds_read_b128 v[116:119], v12 offset:20480
	ds_read_b128 v[120:123], v12 offset:22528
	s_waitcnt lgkmcnt(1)
	v_mfma_f32_16x16x32_f16 v[28:31], v[4:7], v[116:119], v[52:55]
	v_mfma_f32_16x16x32_f16 v[52:55], v[8:11], v[104:107], v[64:67]
	s_nop 2
	v_or_b32_e32 v64, s12, v84
	v_ashrrev_i32_e32 v65, 31, v64
	v_mfma_f32_16x16x32_f16 v[60:63], v[4:7], v[104:107], v[60:63]
	v_mfma_f32_16x16x32_f16 v[44:47], v[4:7], v[108:111], v[56:59]
	s_waitcnt lgkmcnt(0)
	v_mfma_f32_16x16x32_f16 v[12:15], v[4:7], v[120:123], v[48:51]
	v_mfma_f32_16x16x32_f16 v[24:27], v[8:11], v[116:119], v[36:39]
	v_mfma_f32_16x16x32_f16 v[56:59], v[96:99], v[104:107], v[68:71]
	v_mfma_f32_16x16x32_f16 v[36:39], v[96:99], v[108:111], v[20:23]
	v_mfma_f32_16x16x32_f16 v[20:23], v[96:99], v[116:119], v[16:19]
	v_mfma_f32_16x16x32_f16 v[4:7], v[96:99], v[120:123], v[72:75]
	v_lshlrev_b64 v[96:97], 2, v[64:65]
	v_lshl_add_u64 v[64:65], s[2:3], 0, v[96:97]
	v_mfma_f32_16x16x32_f16 v[40:43], v[8:11], v[108:111], v[40:43]
	v_mfma_f32_16x16x32_f16 v[8:11], v[8:11], v[120:123], v[32:35]
	v_mfma_f32_16x16x32_f16 v[32:35], v[100:103], v[108:111], v[92:95]
	s_nop 2
	v_add_u32_e32 v92, s0, v85
	s_mov_b32 s0, 0x8000
	v_mfma_f32_16x16x32_f16 v[48:51], v[100:103], v[104:107], v[80:83]
	v_ashrrev_i32_e32 v93, 31, v92
	v_or_b32_e32 v94, 48, v92
	v_ashrrev_i32_e32 v95, 31, v94
	v_add_co_u32_e32 v80, vcc, s0, v64
	v_mfma_f32_16x16x32_f16 v[16:19], v[100:103], v[116:119], v[0:3]
	s_nop 0
	v_addc_co_u32_e32 v81, vcc, 0, v65, vcc
	global_load_dword v64, v[80:81], off
	v_mfma_f32_16x16x32_f16 v[0:3], v[100:103], v[120:123], v[76:79]
	v_lshl_add_u32 v65, v92, 12, v96
	v_add_u32_e32 v66, 0x1000, v65
	v_add_u32_e32 v67, 0x3000, v65
	v_add_u32_e32 v68, 0x11000, v65
	v_add_u32_e32 v69, 0x13000, v65
	v_add_u32_e32 v70, 0x21000, v65
	v_add_u32_e32 v71, 0x23000, v65
	v_add_u32_e32 v72, 0x31000, v65
	v_add_u32_e32 v73, 0x33000, v65
	v_lshlrev_b32_e32 v176, 3, v92
	v_add_u32_e32 v176, 0x1e200000, v176
	v_mov_b32_e32 v178, s71
	v_mul_u32_u24_e32 v178, 3, v178
	v_add_u32_e32 v178, 1, v178
	v_lshl_add_u32 v177, v178, 12, v96
	global_load_dwordx2 v[136:137], v176, s[30:31] offset:0
	global_load_dwordx2 v[138:139], v176, s[30:31] offset:8
	global_load_dwordx2 v[140:141], v176, s[30:31] offset:16
	global_load_dwordx2 v[142:143], v176, s[30:31] offset:24
	global_load_dwordx2 v[144:145], v176, s[30:31] offset:128
	global_load_dwordx2 v[146:147], v176, s[30:31] offset:136
	global_load_dwordx2 v[148:149], v176, s[30:31] offset:144
	global_load_dwordx2 v[150:151], v176, s[30:31] offset:152
	global_load_dwordx2 v[152:153], v176, s[30:31] offset:256
	global_load_dwordx2 v[154:155], v176, s[30:31] offset:264
	global_load_dwordx2 v[156:157], v176, s[30:31] offset:272
	global_load_dwordx2 v[158:159], v176, s[30:31] offset:280
	global_load_dwordx2 v[160:161], v176, s[30:31] offset:384
	global_load_dwordx2 v[162:163], v176, s[30:31] offset:392
	global_load_dwordx2 v[164:165], v176, s[30:31] offset:400
	global_load_dwordx2 v[166:167], v176, s[30:31] offset:408
	global_load_dword v168, v177, s[24:25] offset:0
	global_load_dword v172, v177, s[26:27] offset:0
	global_load_dword v169, v177, s[24:25] offset:64
	global_load_dword v173, v177, s[26:27] offset:64
	global_load_dword v170, v177, s[24:25] offset:128
	global_load_dword v174, v177, s[26:27] offset:128
	global_load_dword v171, v177, s[24:25] offset:192
	global_load_dword v175, v177, s[26:27] offset:192
	global_load_dword v74, v[80:81], off offset:0
	global_load_dword v75, v[80:81], off offset:64
	global_load_dword v76, v[80:81], off offset:128
	global_load_dword v77, v[80:81], off offset:192
	global_load_dword v78, v66, s[28:29] offset:-4096
	global_load_dword v79, v66, s[28:29] offset:0
	global_load_dword v82, v67, s[28:29] offset:-4096
	global_load_dword v83, v67, s[28:29] offset:0
	global_load_dword v91, v68, s[28:29] offset:-4096
	global_load_dword v93, v68, s[28:29] offset:0
	global_load_dword v94, v69, s[28:29] offset:-4096
	global_load_dword v95, v69, s[28:29] offset:0
	global_load_dword v97, v70, s[28:29] offset:-4096
	global_load_dword v98, v70, s[28:29] offset:0
	global_load_dword v99, v71, s[28:29] offset:-4096
	global_load_dword v100, v71, s[28:29] offset:0
	global_load_dword v101, v72, s[28:29] offset:-4096
	global_load_dword v102, v72, s[28:29] offset:0
	global_load_dword v103, v73, s[28:29] offset:-4096
	global_load_dword v104, v73, s[28:29] offset:0
	global_load_dword v105, v66, s[28:29] offset:-4032
	global_load_dword v106, v66, s[28:29] offset:64
	global_load_dword v107, v67, s[28:29] offset:-4032
	global_load_dword v108, v67, s[28:29] offset:64
	global_load_dword v109, v68, s[28:29] offset:-4032
	global_load_dword v110, v68, s[28:29] offset:64
	global_load_dword v111, v69, s[28:29] offset:-4032
	global_load_dword v112, v69, s[28:29] offset:64
	global_load_dword v116, v70, s[28:29] offset:-4032
	global_load_dword v117, v70, s[28:29] offset:64
	global_load_dword v118, v71, s[28:29] offset:-4032
	global_load_dword v119, v71, s[28:29] offset:64
	global_load_dword v120, v72, s[28:29] offset:-4032
	global_load_dword v121, v72, s[28:29] offset:64
	global_load_dword v122, v73, s[28:29] offset:-4032
	global_load_dword v123, v73, s[28:29] offset:64
	s_waitcnt vmcnt(32)
	v_add_f32_e32 v74, 1.0, v74
	v_add_f32_e32 v75, 1.0, v75
	v_add_f32_e32 v76, 1.0, v76
	v_add_f32_e32 v77, 1.0, v77
	v_mul_f32_e32 v74, 0.5, v74
	v_mul_f32_e32 v75, 0.5, v75
	v_mul_f32_e32 v76, 0.5, v76
	v_mul_f32_e32 v77, 0.5, v77
	s_waitcnt vmcnt(31)
	v_sub_f32_e32 v78, v78, v136
	v_mul_f32_e32 v78, v78, v137
	v_fma_f32 v78, v168, v78, v172
	v_mul_f32_e32 v60, v60, v74
	v_fmac_f32_e32 v60, 0x3fb504f3, v78
	global_load_dword v78, v66, s[28:29] offset:-3968
	global_store_dword v66, v60, s[28:29] offset:-4096
	s_waitcnt vmcnt(32)
	v_sub_f32_e32 v79, v79, v138
	v_mul_f32_e32 v79, v79, v139
	v_fma_f32 v79, v168, v79, v172
	v_mul_f32_e32 v61, v61, v74
	v_fmac_f32_e32 v61, 0x3fb504f3, v79
	global_load_dword v79, v66, s[28:29] offset:128
	global_store_dword v66, v61, s[28:29] offset:0
	s_waitcnt vmcnt(33)
	v_sub_f32_e32 v82, v82, v140
	v_mul_f32_e32 v82, v82, v141
	v_fma_f32 v82, v168, v82, v172
	v_mul_f32_e32 v62, v62, v74
	v_fmac_f32_e32 v62, 0x3fb504f3, v82
	global_load_dword v82, v67, s[28:29] offset:-3968
	global_store_dword v67, v62, s[28:29] offset:-4096
	s_waitcnt vmcnt(34)
	v_sub_f32_e32 v83, v83, v142
	v_mul_f32_e32 v83, v83, v143
	v_fma_f32 v83, v168, v83, v172
	v_mul_f32_e32 v63, v63, v74
	v_fmac_f32_e32 v63, 0x3fb504f3, v83
	global_load_dword v83, v67, s[28:29] offset:128
	global_store_dword v67, v63, s[28:29] offset:0
	s_waitcnt vmcnt(35)
	v_sub_f32_e32 v91, v91, v144
	v_mul_f32_e32 v91, v91, v145
	v_fma_f32 v91, v168, v91, v172
	v_mul_f32_e32 v52, v52, v74
	v_fmac_f32_e32 v52, 0x3fb504f3, v91
	global_load_dword v91, v68, s[28:29] offset:-3968
	global_store_dword v68, v52, s[28:29] offset:-4096
	s_waitcnt vmcnt(36)
	v_sub_f32_e32 v93, v93, v146
	v_mul_f32_e32 v93, v93, v147
	v_fma_f32 v93, v168, v93, v172
	v_mul_f32_e32 v53, v53, v74
	v_fmac_f32_e32 v53, 0x3fb504f3, v93
	global_load_dword v93, v68, s[28:29] offset:128
	global_store_dword v68, v53, s[28:29] offset:0
	s_waitcnt vmcnt(37)
	v_sub_f32_e32 v94, v94, v148
	v_mul_f32_e32 v94, v94, v149
	v_fma_f32 v94, v168, v94, v172
	v_mul_f32_e32 v54, v54, v74
	v_fmac_f32_e32 v54, 0x3fb504f3, v94
	global_load_dword v94, v69, s[28:29] offset:-3968
	global_store_dword v69, v54, s[28:29] offset:-4096
	s_waitcnt vmcnt(38)
	v_sub_f32_e32 v95, v95, v150
	v_mul_f32_e32 v95, v95, v151
	v_fma_f32 v95, v168, v95, v172
	v_mul_f32_e32 v55, v55, v74
	v_fmac_f32_e32 v55, 0x3fb504f3, v95
	global_load_dword v95, v69, s[28:29] offset:128
	global_store_dword v69, v55, s[28:29] offset:0
	s_waitcnt vmcnt(39)
	v_sub_f32_e32 v97, v97, v152
	v_mul_f32_e32 v97, v97, v153
	v_fma_f32 v97, v168, v97, v172
	v_mul_f32_e32 v56, v56, v74
	v_fmac_f32_e32 v56, 0x3fb504f3, v97
	global_load_dword v97, v70, s[28:29] offset:-3968
	global_store_dword v70, v56, s[28:29] offset:-4096
	s_waitcnt vmcnt(40)
	v_sub_f32_e32 v98, v98, v154
	v_mul_f32_e32 v98, v98, v155
	v_fma_f32 v98, v168, v98, v172
	v_mul_f32_e32 v57, v57, v74
	v_fmac_f32_e32 v57, 0x3fb504f3, v98
	global_load_dword v98, v70, s[28:29] offset:128
	global_store_dword v70, v57, s[28:29] offset:0
	s_waitcnt vmcnt(41)
	v_sub_f32_e32 v99, v99, v156
	v_mul_f32_e32 v99, v99, v157
	v_fma_f32 v99, v168, v99, v172
	v_mul_f32_e32 v58, v58, v74
	v_fmac_f32_e32 v58, 0x3fb504f3, v99
	global_load_dword v99, v71, s[28:29] offset:-3968
	global_store_dword v71, v58, s[28:29] offset:-4096
	s_waitcnt vmcnt(42)
	v_sub_f32_e32 v100, v100, v158
	v_mul_f32_e32 v100, v100, v159
	v_fma_f32 v100, v168, v100, v172
	v_mul_f32_e32 v59, v59, v74
	v_fmac_f32_e32 v59, 0x3fb504f3, v100
	global_load_dword v100, v71, s[28:29] offset:128
	global_store_dword v71, v59, s[28:29] offset:0
	s_waitcnt vmcnt(43)
	v_sub_f32_e32 v101, v101, v160
	v_mul_f32_e32 v101, v101, v161
	v_fma_f32 v101, v168, v101, v172
	v_mul_f32_e32 v48, v48, v74
	v_fmac_f32_e32 v48, 0x3fb504f3, v101
	global_load_dword v101, v72, s[28:29] offset:-3968
	global_store_dword v72, v48, s[28:29] offset:-4096
	s_waitcnt vmcnt(44)
	v_sub_f32_e32 v102, v102, v162
	v_mul_f32_e32 v102, v102, v163
	v_fma_f32 v102, v168, v102, v172
	v_mul_f32_e32 v49, v49, v74
	v_fmac_f32_e32 v49, 0x3fb504f3, v102
	global_load_dword v102, v72, s[28:29] offset:128
	global_store_dword v72, v49, s[28:29] offset:0
	s_waitcnt vmcnt(45)
	v_sub_f32_e32 v103, v103, v164
	v_mul_f32_e32 v103, v103, v165
	v_fma_f32 v103, v168, v103, v172
	v_mul_f32_e32 v50, v50, v74
	v_fmac_f32_e32 v50, 0x3fb504f3, v103
	global_load_dword v103, v73, s[28:29] offset:-3968
	global_store_dword v73, v50, s[28:29] offset:-4096
	s_waitcnt vmcnt(46)
	v_sub_f32_e32 v104, v104, v166
	v_mul_f32_e32 v104, v104, v167
	v_fma_f32 v104, v168, v104, v172
	v_mul_f32_e32 v51, v51, v74
	v_fmac_f32_e32 v51, 0x3fb504f3, v104
	global_load_dword v104, v73, s[28:29] offset:128
	global_store_dword v73, v51, s[28:29] offset:0
	s_waitcnt vmcnt(47)
	v_sub_f32_e32 v105, v105, v136
	v_mul_f32_e32 v105, v105, v137
	v_fma_f32 v105, v169, v105, v173
	v_mul_f32_e32 v44, v44, v75
	v_fmac_f32_e32 v44, 0x3fb504f3, v105
	global_load_dword v105, v66, s[28:29] offset:-3904
	global_store_dword v66, v44, s[28:29] offset:-4032
	s_waitcnt vmcnt(48)
	v_sub_f32_e32 v106, v106, v138
	v_mul_f32_e32 v106, v106, v139
	v_fma_f32 v106, v169, v106, v173
	v_mul_f32_e32 v45, v45, v75
	v_fmac_f32_e32 v45, 0x3fb504f3, v106
	global_load_dword v106, v66, s[28:29] offset:192
	global_store_dword v66, v45, s[28:29] offset:64
	s_waitcnt vmcnt(49)
	v_sub_f32_e32 v107, v107, v140
	v_mul_f32_e32 v107, v107, v141
	v_fma_f32 v107, v169, v107, v173
	v_mul_f32_e32 v46, v46, v75
	v_fmac_f32_e32 v46, 0x3fb504f3, v107
	global_load_dword v107, v67, s[28:29] offset:-3904
	global_store_dword v67, v46, s[28:29] offset:-4032
	s_waitcnt vmcnt(50)
	v_sub_f32_e32 v108, v108, v142
	v_mul_f32_e32 v108, v108, v143
	v_fma_f32 v108, v169, v108, v173
	v_mul_f32_e32 v47, v47, v75
	v_fmac_f32_e32 v47, 0x3fb504f3, v108
	global_load_dword v108, v67, s[28:29] offset:192
	global_store_dword v67, v47, s[28:29] offset:64
	s_waitcnt vmcnt(51)
	v_sub_f32_e32 v109, v109, v144
	v_mul_f32_e32 v109, v109, v145
	v_fma_f32 v109, v169, v109, v173
	v_mul_f32_e32 v40, v40, v75
	v_fmac_f32_e32 v40, 0x3fb504f3, v109
	global_load_dword v109, v68, s[28:29] offset:-3904
	global_store_dword v68, v40, s[28:29] offset:-4032
	s_waitcnt vmcnt(52)
	v_sub_f32_e32 v110, v110, v146
	v_mul_f32_e32 v110, v110, v147
	v_fma_f32 v110, v169, v110, v173
	v_mul_f32_e32 v41, v41, v75
	v_fmac_f32_e32 v41, 0x3fb504f3, v110
	global_load_dword v110, v68, s[28:29] offset:192
	global_store_dword v68, v41, s[28:29] offset:64
	s_waitcnt vmcnt(53)
	v_sub_f32_e32 v111, v111, v148
	v_mul_f32_e32 v111, v111, v149
	v_fma_f32 v111, v169, v111, v173
	v_mul_f32_e32 v42, v42, v75
	v_fmac_f32_e32 v42, 0x3fb504f3, v111
	global_load_dword v111, v69, s[28:29] offset:-3904
	global_store_dword v69, v42, s[28:29] offset:-4032
	s_waitcnt vmcnt(54)
	v_sub_f32_e32 v112, v112, v150
	v_mul_f32_e32 v112, v112, v151
	v_fma_f32 v112, v169, v112, v173
	v_mul_f32_e32 v43, v43, v75
	v_fmac_f32_e32 v43, 0x3fb504f3, v112
	global_load_dword v112, v69, s[28:29] offset:192
	global_store_dword v69, v43, s[28:29] offset:64
	s_waitcnt vmcnt(55)
	v_sub_f32_e32 v116, v116, v152
	v_mul_f32_e32 v116, v116, v153
	v_fma_f32 v116, v169, v116, v173
	v_mul_f32_e32 v36, v36, v75
	v_fmac_f32_e32 v36, 0x3fb504f3, v116
	global_load_dword v116, v70, s[28:29] offset:-3904
	global_store_dword v70, v36, s[28:29] offset:-4032
	s_waitcnt vmcnt(56)
	v_sub_f32_e32 v117, v117, v154
	v_mul_f32_e32 v117, v117, v155
	v_fma_f32 v117, v169, v117, v173
	v_mul_f32_e32 v37, v37, v75
	v_fmac_f32_e32 v37, 0x3fb504f3, v117
	global_load_dword v117, v70, s[28:29] offset:192
	global_store_dword v70, v37, s[28:29] offset:64
	s_waitcnt vmcnt(57)
	v_sub_f32_e32 v118, v118, v156
	v_mul_f32_e32 v118, v118, v157
	v_fma_f32 v118, v169, v118, v173
	v_mul_f32_e32 v38, v38, v75
	v_fmac_f32_e32 v38, 0x3fb504f3, v118
	global_load_dword v118, v71, s[28:29] offset:-3904
	global_store_dword v71, v38, s[28:29] offset:-4032
	s_waitcnt vmcnt(58)
	v_sub_f32_e32 v119, v119, v158
	v_mul_f32_e32 v119, v119, v159
	v_fma_f32 v119, v169, v119, v173
	v_mul_f32_e32 v39, v39, v75
	v_fmac_f32_e32 v39, 0x3fb504f3, v119
	global_load_dword v119, v71, s[28:29] offset:192
	global_store_dword v71, v39, s[28:29] offset:64
	s_waitcnt vmcnt(59)
	v_sub_f32_e32 v120, v120, v160
	v_mul_f32_e32 v120, v120, v161
	v_fma_f32 v120, v169, v120, v173
	v_mul_f32_e32 v32, v32, v75
	v_fmac_f32_e32 v32, 0x3fb504f3, v120
	global_load_dword v120, v72, s[28:29] offset:-3904
	global_store_dword v72, v32, s[28:29] offset:-4032
	s_waitcnt vmcnt(60)
	v_sub_f32_e32 v121, v121, v162
	v_mul_f32_e32 v121, v121, v163
	v_fma_f32 v121, v169, v121, v173
	v_mul_f32_e32 v33, v33, v75
	v_fmac_f32_e32 v33, 0x3fb504f3, v121
	global_load_dword v121, v72, s[28:29] offset:192
	global_store_dword v72, v33, s[28:29] offset:64
	s_waitcnt vmcnt(61)
	v_sub_f32_e32 v122, v122, v164
	v_mul_f32_e32 v122, v122, v165
	v_fma_f32 v122, v169, v122, v173
	v_mul_f32_e32 v34, v34, v75
	v_fmac_f32_e32 v34, 0x3fb504f3, v122
	global_load_dword v122, v73, s[28:29] offset:-3904
	global_store_dword v73, v34, s[28:29] offset:-4032
	s_waitcnt vmcnt(62)
	v_sub_f32_e32 v123, v123, v166
	v_mul_f32_e32 v123, v123, v167
	v_fma_f32 v123, v169, v123, v173
	v_mul_f32_e32 v35, v35, v75
	v_fmac_f32_e32 v35, 0x3fb504f3, v123
	global_load_dword v123, v73, s[28:29] offset:192
	global_store_dword v73, v35, s[28:29] offset:64
	s_waitcnt vmcnt(63)
	v_sub_f32_e32 v78, v78, v136
	v_mul_f32_e32 v78, v78, v137
	v_fma_f32 v78, v170, v78, v174
	v_mul_f32_e32 v28, v28, v76
	v_fmac_f32_e32 v28, 0x3fb504f3, v78
	global_store_dword v66, v28, s[28:29] offset:-3968
	s_waitcnt vmcnt(62)
	v_sub_f32_e32 v79, v79, v138
	v_mul_f32_e32 v79, v79, v139
	v_fma_f32 v79, v170, v79, v174
	v_mul_f32_e32 v29, v29, v76
	v_fmac_f32_e32 v29, 0x3fb504f3, v79
	global_store_dword v66, v29, s[28:29] offset:128
	s_waitcnt vmcnt(61)
	v_sub_f32_e32 v82, v82, v140
	v_mul_f32_e32 v82, v82, v141
	v_fma_f32 v82, v170, v82, v174
	v_mul_f32_e32 v30, v30, v76
	v_fmac_f32_e32 v30, 0x3fb504f3, v82
	global_store_dword v67, v30, s[28:29] offset:-3968
	s_waitcnt vmcnt(60)
	v_sub_f32_e32 v83, v83, v142
	v_mul_f32_e32 v83, v83, v143
	v_fma_f32 v83, v170, v83, v174
	v_mul_f32_e32 v31, v31, v76
	v_fmac_f32_e32 v31, 0x3fb504f3, v83
	global_store_dword v67, v31, s[28:29] offset:128
	s_waitcnt vmcnt(59)
	v_sub_f32_e32 v91, v91, v144
	v_mul_f32_e32 v91, v91, v145
	v_fma_f32 v91, v170, v91, v174
	v_mul_f32_e32 v24, v24, v76
	v_fmac_f32_e32 v24, 0x3fb504f3, v91
	global_store_dword v68, v24, s[28:29] offset:-3968
	s_waitcnt vmcnt(58)
	v_sub_f32_e32 v93, v93, v146
	v_mul_f32_e32 v93, v93, v147
	v_fma_f32 v93, v170, v93, v174
	v_mul_f32_e32 v25, v25, v76
	v_fmac_f32_e32 v25, 0x3fb504f3, v93
	global_store_dword v68, v25, s[28:29] offset:128
	s_waitcnt vmcnt(57)
	v_sub_f32_e32 v94, v94, v148
	v_mul_f32_e32 v94, v94, v149
	v_fma_f32 v94, v170, v94, v174
	v_mul_f32_e32 v26, v26, v76
	v_fmac_f32_e32 v26, 0x3fb504f3, v94
	global_store_dword v69, v26, s[28:29] offset:-3968
	s_waitcnt vmcnt(56)
	v_sub_f32_e32 v95, v95, v150
	v_mul_f32_e32 v95, v95, v151
	v_fma_f32 v95, v170, v95, v174
	v_mul_f32_e32 v27, v27, v76
	v_fmac_f32_e32 v27, 0x3fb504f3, v95
	global_store_dword v69, v27, s[28:29] offset:128
	s_waitcnt vmcnt(55)
	v_sub_f32_e32 v97, v97, v152
	v_mul_f32_e32 v97, v97, v153
	v_fma_f32 v97, v170, v97, v174
	v_mul_f32_e32 v20, v20, v76
	v_fmac_f32_e32 v20, 0x3fb504f3, v97
	global_store_dword v70, v20, s[28:29] offset:-3968
	s_waitcnt vmcnt(54)
	v_sub_f32_e32 v98, v98, v154
	v_mul_f32_e32 v98, v98, v155
	v_fma_f32 v98, v170, v98, v174
	v_mul_f32_e32 v21, v21, v76
	v_fmac_f32_e32 v21, 0x3fb504f3, v98
	global_store_dword v70, v21, s[28:29] offset:128
	s_waitcnt vmcnt(53)
	v_sub_f32_e32 v99, v99, v156
	v_mul_f32_e32 v99, v99, v157
	v_fma_f32 v99, v170, v99, v174
	v_mul_f32_e32 v22, v22, v76
	v_fmac_f32_e32 v22, 0x3fb504f3, v99
	global_store_dword v71, v22, s[28:29] offset:-3968
	s_waitcnt vmcnt(52)
	v_sub_f32_e32 v100, v100, v158
	v_mul_f32_e32 v100, v100, v159
	v_fma_f32 v100, v170, v100, v174
	v_mul_f32_e32 v23, v23, v76
	v_fmac_f32_e32 v23, 0x3fb504f3, v100
	global_store_dword v71, v23, s[28:29] offset:128
	s_waitcnt vmcnt(51)
	v_sub_f32_e32 v101, v101, v160
	v_mul_f32_e32 v101, v101, v161
	v_fma_f32 v101, v170, v101, v174
	v_mul_f32_e32 v16, v16, v76
	v_fmac_f32_e32 v16, 0x3fb504f3, v101
	global_store_dword v72, v16, s[28:29] offset:-3968
	s_waitcnt vmcnt(50)
	v_sub_f32_e32 v102, v102, v162
	v_mul_f32_e32 v102, v102, v163
	v_fma_f32 v102, v170, v102, v174
	v_mul_f32_e32 v17, v17, v76
	v_fmac_f32_e32 v17, 0x3fb504f3, v102
	global_store_dword v72, v17, s[28:29] offset:128
	s_waitcnt vmcnt(49)
	v_sub_f32_e32 v103, v103, v164
	v_mul_f32_e32 v103, v103, v165
	v_fma_f32 v103, v170, v103, v174
	v_mul_f32_e32 v18, v18, v76
	v_fmac_f32_e32 v18, 0x3fb504f3, v103
	global_store_dword v73, v18, s[28:29] offset:-3968
	s_waitcnt vmcnt(48)
	v_sub_f32_e32 v104, v104, v166
	v_mul_f32_e32 v104, v104, v167
	v_fma_f32 v104, v170, v104, v174
	v_mul_f32_e32 v19, v19, v76
	v_fmac_f32_e32 v19, 0x3fb504f3, v104
	global_store_dword v73, v19, s[28:29] offset:128
	s_waitcnt vmcnt(47)
	v_sub_f32_e32 v105, v105, v136
	v_mul_f32_e32 v105, v105, v137
	v_fma_f32 v105, v171, v105, v175
	v_mul_f32_e32 v12, v12, v77
	v_fmac_f32_e32 v12, 0x3fb504f3, v105
	global_store_dword v66, v12, s[28:29] offset:-3904
	s_waitcnt vmcnt(46)
	v_sub_f32_e32 v106, v106, v138
	v_mul_f32_e32 v106, v106, v139
	v_fma_f32 v106, v171, v106, v175
	v_mul_f32_e32 v13, v13, v77
	v_fmac_f32_e32 v13, 0x3fb504f3, v106
	global_store_dword v66, v13, s[28:29] offset:192
	s_waitcnt vmcnt(45)
	v_sub_f32_e32 v107, v107, v140
	v_mul_f32_e32 v107, v107, v141
	v_fma_f32 v107, v171, v107, v175
	v_mul_f32_e32 v14, v14, v77
	v_fmac_f32_e32 v14, 0x3fb504f3, v107
	global_store_dword v67, v14, s[28:29] offset:-3904
	s_waitcnt vmcnt(44)
	v_sub_f32_e32 v108, v108, v142
	v_mul_f32_e32 v108, v108, v143
	v_fma_f32 v108, v171, v108, v175
	v_mul_f32_e32 v15, v15, v77
	v_fmac_f32_e32 v15, 0x3fb504f3, v108
	global_store_dword v67, v15, s[28:29] offset:192
	s_waitcnt vmcnt(43)
	v_sub_f32_e32 v109, v109, v144
	v_mul_f32_e32 v109, v109, v145
	v_fma_f32 v109, v171, v109, v175
	v_mul_f32_e32 v8, v8, v77
	v_fmac_f32_e32 v8, 0x3fb504f3, v109
	global_store_dword v68, v8, s[28:29] offset:-3904
	s_waitcnt vmcnt(42)
	v_sub_f32_e32 v110, v110, v146
	v_mul_f32_e32 v110, v110, v147
	v_fma_f32 v110, v171, v110, v175
	v_mul_f32_e32 v9, v9, v77
	v_fmac_f32_e32 v9, 0x3fb504f3, v110
	global_store_dword v68, v9, s[28:29] offset:192
	s_waitcnt vmcnt(41)
	v_sub_f32_e32 v111, v111, v148
	v_mul_f32_e32 v111, v111, v149
	v_fma_f32 v111, v171, v111, v175
	v_mul_f32_e32 v10, v10, v77
	v_fmac_f32_e32 v10, 0x3fb504f3, v111
	global_store_dword v69, v10, s[28:29] offset:-3904
	s_waitcnt vmcnt(40)
	v_sub_f32_e32 v112, v112, v150
	v_mul_f32_e32 v112, v112, v151
	v_fma_f32 v112, v171, v112, v175
	v_mul_f32_e32 v11, v11, v77
	v_fmac_f32_e32 v11, 0x3fb504f3, v112
	global_store_dword v69, v11, s[28:29] offset:192
	s_waitcnt vmcnt(39)
	v_sub_f32_e32 v116, v116, v152
	v_mul_f32_e32 v116, v116, v153
	v_fma_f32 v116, v171, v116, v175
	v_mul_f32_e32 v4, v4, v77
	v_fmac_f32_e32 v4, 0x3fb504f3, v116
	global_store_dword v70, v4, s[28:29] offset:-3904
	s_waitcnt vmcnt(38)
	v_sub_f32_e32 v117, v117, v154
	v_mul_f32_e32 v117, v117, v155
	v_fma_f32 v117, v171, v117, v175
	v_mul_f32_e32 v5, v5, v77
	v_fmac_f32_e32 v5, 0x3fb504f3, v117
	global_store_dword v70, v5, s[28:29] offset:192
	s_waitcnt vmcnt(37)
	v_sub_f32_e32 v118, v118, v156
	v_mul_f32_e32 v118, v118, v157
	v_fma_f32 v118, v171, v118, v175
	v_mul_f32_e32 v6, v6, v77
	v_fmac_f32_e32 v6, 0x3fb504f3, v118
	global_store_dword v71, v6, s[28:29] offset:-3904
	s_waitcnt vmcnt(36)
	v_sub_f32_e32 v119, v119, v158
	v_mul_f32_e32 v119, v119, v159
	v_fma_f32 v119, v171, v119, v175
	v_mul_f32_e32 v7, v7, v77
	v_fmac_f32_e32 v7, 0x3fb504f3, v119
	global_store_dword v71, v7, s[28:29] offset:192
	s_waitcnt vmcnt(35)
	v_sub_f32_e32 v120, v120, v160
	v_mul_f32_e32 v120, v120, v161
	v_fma_f32 v120, v171, v120, v175
	v_mul_f32_e32 v0, v0, v77
	v_fmac_f32_e32 v0, 0x3fb504f3, v120
	global_store_dword v72, v0, s[28:29] offset:-3904
	s_waitcnt vmcnt(34)
	v_sub_f32_e32 v121, v121, v162
	v_mul_f32_e32 v121, v121, v163
	v_fma_f32 v121, v171, v121, v175
	v_mul_f32_e32 v1, v1, v77
	v_fmac_f32_e32 v1, 0x3fb504f3, v121
	global_store_dword v72, v1, s[28:29] offset:192
	s_waitcnt vmcnt(33)
	v_sub_f32_e32 v122, v122, v164
	v_mul_f32_e32 v122, v122, v165
	v_fma_f32 v122, v171, v122, v175
	v_mul_f32_e32 v2, v2, v77
	v_fmac_f32_e32 v2, 0x3fb504f3, v122
	global_store_dword v73, v2, s[28:29] offset:-3904
	s_waitcnt vmcnt(32)
	v_sub_f32_e32 v123, v123, v166
	v_mul_f32_e32 v123, v123, v167
	v_fma_f32 v123, v171, v123, v175
	v_mul_f32_e32 v3, v3, v77
	v_fmac_f32_e32 v3, 0x3fb504f3, v123
	global_store_dword v73, v3, s[28:29] offset:192
	s_cbranch_scc0 .LBB0_649

.LBB0_664:
	s_or_b64 exec, exec, s[12:13]
	global_load_dwordx4 v[48:51], v[70:71], off offset:-2048
	s_waitcnt vmcnt(0)
	v_add_f32_e32 v52, 0, v48
	v_add_f32_e32 v52, v52, v49
	v_add_f32_e32 v52, v52, v50
	v_add_f32_e32 v56, v52, v51
	global_load_dwordx4 v[52:55], v[70:71], off offset:-1024
	s_waitcnt vmcnt(0)
	v_add_f32_e32 v56, v56, v52
	v_add_f32_e32 v56, v56, v53
	v_add_f32_e32 v56, v56, v54
	v_add_f32_e32 v60, v56, v55
	global_load_dwordx4 v[56:59], v[70:71], off
	s_waitcnt vmcnt(0)
	v_add_f32_e32 v60, v60, v56
	v_add_f32_e32 v60, v60, v57
	v_add_f32_e32 v60, v60, v58
	v_add_f32_e32 v65, v60, v59
	global_load_dwordx4 v[60:63], v[70:71], off offset:1024
	s_waitcnt vmcnt(0)
	v_add_f32_e32 v65, v65, v60
	v_add_f32_e32 v65, v65, v61
	v_add_f32_e32 v65, v65, v62
	v_add_f32_e32 v65, v65, v63
	ds_bpermute_b32 v96, v89, v65
	s_waitcnt lgkmcnt(0)
	v_add_f32_e32 v65, v65, v96
	ds_bpermute_b32 v96, v90, v65
	s_waitcnt lgkmcnt(0)
	v_add_f32_e32 v65, v65, v96
	ds_bpermute_b32 v96, v91, v65
	s_waitcnt lgkmcnt(0)
	v_add_f32_e32 v65, v65, v96
	ds_bpermute_b32 v96, v92, v65
	s_waitcnt lgkmcnt(0)
	v_add_f32_e32 v65, v65, v96
	ds_bpermute_b32 v96, v93, v65
	s_waitcnt lgkmcnt(0)
	v_add_f32_e32 v65, v65, v96
	ds_bpermute_b32 v96, v94, v65
	s_waitcnt lgkmcnt(0)
	v_add_f32_e32 v65, v65, v96
	v_mul_f32_e32 v96, 0x3a800000, v65
	v_mov_b32_e32 v252, v96
	v_pk_add_f32 v[48:49], v[48:49], v[96:97] op_sel_hi:[1,0] neg_lo:[0,1] neg_hi:[0,1]
	v_pk_add_f32 v[50:51], v[50:51], v[96:97] op_sel_hi:[1,0] neg_lo:[0,1] neg_hi:[0,1]
	v_pk_mul_f32 v[98:99], v[48:49], v[48:49]
	v_pk_mul_f32 v[100:101], v[50:51], v[50:51]
	v_add_f32_e32 v65, v98, v99
	v_pk_add_f32 v[52:53], v[52:53], v[96:97] op_sel_hi:[1,0] neg_lo:[0,1] neg_hi:[0,1]
	v_add_f32_e32 v65, v100, v65
	v_pk_mul_f32 v[102:103], v[52:53], v[52:53]
	v_add_f32_e32 v65, v101, v65
	v_pk_add_f32 v[54:55], v[54:55], v[96:97] op_sel_hi:[1,0] neg_lo:[0,1] neg_hi:[0,1]
	v_add_f32_e32 v65, v102, v65
	v_pk_mul_f32 v[104:105], v[54:55], v[54:55]
	v_add_f32_e32 v65, v103, v65
	v_pk_add_f32 v[106:107], v[56:57], v[96:97] op_sel_hi:[1,0] neg_lo:[0,1] neg_hi:[0,1]
	v_add_f32_e32 v65, v104, v65
	v_pk_mul_f32 v[56:57], v[106:107], v[106:107]
	v_add_f32_e32 v65, v105, v65
	v_pk_add_f32 v[108:109], v[58:59], v[96:97] op_sel_hi:[1,0] neg_lo:[0,1] neg_hi:[0,1]
	v_add_f32_e32 v56, v56, v65
	v_pk_mul_f32 v[58:59], v[108:109], v[108:109]
	v_add_f32_e32 v56, v57, v56
	v_pk_add_f32 v[110:111], v[60:61], v[96:97] op_sel_hi:[1,0] neg_lo:[0,1] neg_hi:[0,1]
	v_add_f32_e32 v56, v58, v56
	v_pk_mul_f32 v[60:61], v[110:111], v[110:111]
	v_add_f32_e32 v56, v59, v56
	v_pk_add_f32 v[96:97], v[62:63], v[96:97] op_sel_hi:[1,0] neg_lo:[0,1] neg_hi:[0,1]
	v_add_f32_e32 v56, v60, v56
	v_pk_mul_f32 v[62:63], v[96:97], v[96:97]
	v_add_f32_e32 v56, v61, v56
	v_add_f32_e32 v56, v62, v56
	v_add_f32_e32 v56, v63, v56
	ds_bpermute_b32 v57, v89, v56
	s_waitcnt lgkmcnt(0)
	v_add_f32_e32 v56, v56, v57
	ds_bpermute_b32 v57, v90, v56
	s_waitcnt lgkmcnt(0)
	v_add_f32_e32 v56, v56, v57
	ds_bpermute_b32 v57, v91, v56
	s_waitcnt lgkmcnt(0)
	v_add_f32_e32 v56, v56, v57
	ds_bpermute_b32 v57, v92, v56
	s_waitcnt lgkmcnt(0)
	v_add_f32_e32 v56, v56, v57
	ds_bpermute_b32 v57, v93, v56
	s_waitcnt lgkmcnt(0)
	v_add_f32_e32 v56, v56, v57
	ds_bpermute_b32 v57, v94, v56
	s_waitcnt lgkmcnt(0)
	v_add_f32_e32 v56, v56, v57
	v_fmamk_f32 v56, v56, 0x3a800000, v184
	v_cmp_gt_f32_e32 vcc, s49, v56
	v_mul_f32_e32 v57, 0x4b800000, v56
	s_nop 0
	v_cndmask_b32_e32 v56, v56, v57, vcc
	v_rsq_f32_e32 v56, v56
	s_nop 0
	v_mul_f32_e32 v57, 0x45800000, v56
	v_cndmask_b32_e32 v98, v56, v57, vcc
	v_mov_b32_e32 v253, v98
	v_lshlrev_b32_e32 v254, 3, v64
	v_add_u32_e32 v254, 0x1e200000, v254
	s_mov_b64 exec, 1
	global_store_dwordx2 v254, v[252:253], s[30:31]
	s_mov_b64 exec, -1
	v_pk_mul_f32 v[48:49], v[48:49], v[98:99] op_sel_hi:[1,0]
	s_andn2_b64 vcc, exec, s[2:3]
	v_pk_fma_f32 v[60:61], v[0:1], v[48:49], v[8:9]
	v_pk_mul_f32 v[48:49], v[50:51], v[98:99] op_sel_hi:[1,0]
	v_pk_mul_f32 v[50:51], v[96:97], v[98:99] op_sel_hi:[1,0]
	v_pk_fma_f32 v[62:63], v[2:3], v[48:49], v[10:11]
	v_pk_mul_f32 v[48:49], v[52:53], v[98:99] op_sel_hi:[1,0]
	v_pk_fma_f32 v[50:51], v[22:23], v[50:51], v[30:31]
	v_pk_fma_f32 v[56:57], v[4:5], v[48:49], v[12:13]
	v_pk_mul_f32 v[48:49], v[54:55], v[98:99] op_sel_hi:[1,0]
	s_nop 0
	v_pk_fma_f32 v[58:59], v[6:7], v[48:49], v[14:15]
	v_pk_mul_f32 v[48:49], v[106:107], v[98:99] op_sel_hi:[1,0]
	s_nop 0
	v_pk_fma_f32 v[52:53], v[16:17], v[48:49], v[24:25]
	v_pk_mul_f32 v[48:49], v[108:109], v[98:99] op_sel_hi:[1,0]
	s_nop 0
	v_pk_fma_f32 v[54:55], v[18:19], v[48:49], v[26:27]
	v_pk_mul_f32 v[48:49], v[110:111], v[98:99] op_sel_hi:[1,0]
	s_nop 0
	v_pk_fma_f32 v[48:49], v[20:21], v[48:49], v[28:29]
	v_mov_b32_e32 v255, s71
	v_cmp_eq_u32_e64 s[100:101], 1, v255
	s_nop 1
	s_mov_b64 exec, s[100:101]
	global_store_dwordx4 v[70:71], v[60:63], off offset:-2048
	global_store_dwordx4 v[70:71], v[56:59], off offset:-1024
	global_store_dwordx4 v[70:71], v[52:55], off
	global_store_dwordx4 v[70:71], v[48:51], off offset:1024
	s_mov_b64 exec, -1
	s_cbranch_vccz .LBB0_668
